# mem_attn: drop barriers between non-staging items; grid barrier: waiters poll global generation word directly (no per-XCD release hop)
# speedup vs baseline: 1.0039x; 1.0039x over previous
; #define LAS __attribute__((address_space(3)))
; DI f32x4 mfma16(bf16x8 a, bf16x8 b, f32x4 c) { return __builtin_amdgcn_mfma_f32_16x16x32_bf16(a, b, c, 0, 0, 0); }
; DI void mem_attn_item(ldsp lds, const bf16_t* proj, int ldp, int qmcol, int gatecol, const bf16_t* kv, bf16_t* branch, int b0, int item, int tid, int wid, int lane, const bool stage = true) {
;     ...
;     if (stage)
; #pragma unroll
;     for (int i = 0; i < 4; ++i) {
;         const int e = tid + i * 512, row = e >> 3, ch = e & 7;
;         const u32x4 kx = *(const u32x4*)(kvb + (size_t)row * 2048 + ch * 8);
;         const u32x4 vx = *(const u32x4*)(kvb + (size_t)row * 2048 + 256 + ch * 8);
;         *(LAS u32x4*)(Kb + row * KS + ch * 16) = kx;
;         *(LAS u32x4*)(Vb + row * KS + ch * 16) = vx;
;     }
;     const int li = lane & 15, quad = lane >> 4;
;     const int tq = 128 * qt + 16 * wid + li;
;     const size_t prow = (size_t)bl * 2048 + tq;
;     bf16x8 qf[2];
; #pragma unroll
;     for (int ks = 0; ks < 2; ++ks) qf[ks] = *(const bf16x8*)(proj + prow * ldp + qmcol + hm * 64 + ks * 32 + quad * 8);
;     u32x2 gtv[4];
; #pragma unroll
;     for (int dt = 0; dt < 4; ++dt) gtv[dt] = *(const u32x2*)(proj + prow * ldp + gatecol + 768 + hm * 64 + quad * 4 + dt * 16);
;     __syncthreads();
;     f32x4 sacc[16];
; #pragma unroll
;     for (int t = 0; t < 16; ++t) {
;         sacc[t] = (f32x4){0.f, 0.f, 0.f, 0.f};
;         const ldsp ka = Kb + (16 * t + li) * KS + quad * 16;
; #pragma unroll
;         for (int ks = 0; ks < 2; ++ks) sacc[t] = mfma16(lds_rd8(ka + ks * 64), qf[ks], sacc[t]);
;     }
.LBB0_444:
	v_readlane_b32 s15, v252, 2
	s_or_b32 s14, s14, s15
	s_lshl_b32 s14, s14, 7
	s_and_b32 s14, s14, 0x780
	v_add_u32_e32 v94, s14, v13
	v_ashrrev_i32_e32 v95, 31, v94
	v_lshlrev_b64 v[0:1], 14, v[94:95]
	v_lshl_add_u64 v[0:1], s[38:39], 0, v[0:1]
	v_lshlrev_b32_e32 v2, 1, v30
	v_mov_b32_e32 v3, v12
	v_lshl_add_u64 v[4:5], v[0:1], 0, s[0:1]
	v_lshl_add_u64 v[0:1], v[4:5], 0, v[2:3]
	s_movk_i32 s15, 0x3000
	v_lshl_add_u64 v[2:3], v[0:1], 0, s[76:77]
	v_add_co_u32_e32 v0, vcc, s15, v0
	v_mov_b32_e32 v85, v12
	s_nop 0
	v_addc_co_u32_e32 v1, vcc, 0, v1, vcc
	global_load_dwordx4 v[70:73], v[0:1], off offset:1536
	s_nop 0
	global_load_dwordx4 v[0:3], v[2:3], off offset:64
	v_lshl_add_u64 v[4:5], v[4:5], 0, v[84:85]
	v_lshl_add_u64 v[6:7], v[4:5], 0, s[80:81]
	v_add_co_u32_e32 v4, vcc, s15, v4
	s_mov_b32 s15, 0xff800000
	s_nop 0
	v_addc_co_u32_e32 v5, vcc, 0, v5, vcc
	global_load_dwordx2 v[92:93], v[4:5], off offset:3584
	global_load_dwordx2 v[90:91], v[6:7], off offset:32
	global_load_dwordx2 v[88:89], v[6:7], off offset:64
	global_load_dwordx2 v[86:87], v[6:7], off offset:96
	s_waitcnt lgkmcnt(0)
	s_cmp_lg_u64 s[40:41], 0
	s_cbranch_scc1 .Lma_nobar_dil
	s_barrier
.Lma_nobar_dil:
	ds_read_b128 v[4:7], v102
	ds_read_b128 v[8:11], v102 offset:64
	s_mov_b32 s14, 1
	s_waitcnt vmcnt(5) lgkmcnt(1)
	v_mfma_f32_16x16x32_bf16 v[4:7], v[4:7], v[70:73], 0
	ds_read_b128 v[108:111], v102 offset:32320
	s_waitcnt vmcnt(4) lgkmcnt(1)
	v_mfma_f32_16x16x32_bf16 v[66:69], v[8:11], v[0:3], v[4:7]
	ds_read_b128 v[8:11], v102 offset:2368
	s_nop 3
	ds_read_b128 v[4:7], v102 offset:2304
	s_waitcnt lgkmcnt(0)
	v_mfma_f32_16x16x32_bf16 v[4:7], v[4:7], v[70:73], 0
	v_mfma_f32_16x16x32_bf16 v[62:65], v[8:11], v[0:3], v[4:7]
	ds_read_b128 v[8:11], v102 offset:4672
	s_nop 5
	ds_read_b128 v[4:7], v102 offset:4608
	s_waitcnt lgkmcnt(0)
	v_mfma_f32_16x16x32_bf16 v[4:7], v[4:7], v[70:73], 0
	v_mfma_f32_16x16x32_bf16 v[58:61], v[8:11], v[0:3], v[4:7]
	ds_read_b128 v[8:11], v103 offset:64
	s_nop 5
	ds_read_b128 v[4:7], v103
	s_waitcnt lgkmcnt(0)
	v_mfma_f32_16x16x32_bf16 v[4:7], v[4:7], v[70:73], 0
	v_mfma_f32_16x16x32_bf16 v[54:57], v[8:11], v[0:3], v[4:7]
	ds_read_b128 v[8:11], v102 offset:9280
	s_nop 5
	ds_read_b128 v[4:7], v102 offset:9216
	s_waitcnt lgkmcnt(0)
	v_mfma_f32_16x16x32_bf16 v[4:7], v[4:7], v[70:73], 0
	v_mfma_f32_16x16x32_bf16 v[50:53], v[8:11], v[0:3], v[4:7]
	ds_read_b128 v[8:11], v102 offset:11584
	s_nop 5
	ds_read_b128 v[4:7], v102 offset:11520
	s_waitcnt lgkmcnt(0)
	v_mfma_f32_16x16x32_bf16 v[4:7], v[4:7], v[70:73], 0
	v_mfma_f32_16x16x32_bf16 v[46:49], v[8:11], v[0:3], v[4:7]
	ds_read_b128 v[8:11], v102 offset:13888
	s_nop 5
	ds_read_b128 v[4:7], v102 offset:13824
	s_waitcnt lgkmcnt(0)
	v_mfma_f32_16x16x32_bf16 v[4:7], v[4:7], v[70:73], 0
	v_mfma_f32_16x16x32_bf16 v[42:45], v[8:11], v[0:3], v[4:7]
	ds_read_b128 v[8:11], v104 offset:64
	s_nop 5
	ds_read_b128 v[4:7], v104
	s_waitcnt lgkmcnt(0)
	v_mfma_f32_16x16x32_bf16 v[4:7], v[4:7], v[70:73], 0
	v_mfma_f32_16x16x32_bf16 v[38:41], v[8:11], v[0:3], v[4:7]
	ds_read_b128 v[8:11], v102 offset:18496
	s_nop 5
	ds_read_b128 v[4:7], v102 offset:18432
	s_waitcnt lgkmcnt(0)
	v_mfma_f32_16x16x32_bf16 v[4:7], v[4:7], v[70:73], 0
	v_mfma_f32_16x16x32_bf16 v[34:37], v[8:11], v[0:3], v[4:7]
	ds_read_b128 v[8:11], v102 offset:20800
	s_nop 5
	ds_read_b128 v[4:7], v102 offset:20736
	s_waitcnt lgkmcnt(0)
	v_mfma_f32_16x16x32_bf16 v[4:7], v[4:7], v[70:73], 0
	v_mfma_f32_16x16x32_bf16 v[26:29], v[8:11], v[0:3], v[4:7]
	ds_read_b128 v[8:11], v102 offset:23104
	s_nop 5
	ds_read_b128 v[4:7], v102 offset:23040
	s_waitcnt lgkmcnt(0)
	v_mfma_f32_16x16x32_bf16 v[4:7], v[4:7], v[70:73], 0
	v_mfma_f32_16x16x32_bf16 v[22:25], v[8:11], v[0:3], v[4:7]
	ds_read_b128 v[8:11], v105 offset:64
	s_nop 5
	ds_read_b128 v[4:7], v105
	s_waitcnt lgkmcnt(0)
	v_mfma_f32_16x16x32_bf16 v[4:7], v[4:7], v[70:73], 0
	v_mfma_f32_16x16x32_bf16 v[14:17], v[8:11], v[0:3], v[4:7]
	ds_read_b128 v[8:11], v102 offset:27712
	s_nop 5
	ds_read_b128 v[4:7], v102 offset:27648
	s_waitcnt lgkmcnt(0)
	v_mfma_f32_16x16x32_bf16 v[4:7], v[4:7], v[70:73], 0
	v_mfma_f32_16x16x32_bf16 v[18:21], v[8:11], v[0:3], v[4:7]
	ds_read_b128 v[8:11], v102 offset:30016
	s_nop 5
	ds_read_b128 v[4:7], v102 offset:29952
	s_waitcnt lgkmcnt(0)
	v_mfma_f32_16x16x32_bf16 v[4:7], v[4:7], v[70:73], 0
	v_mfma_f32_16x16x32_bf16 v[8:11], v[8:11], v[0:3], v[4:7]
	s_nop 6
	ds_read_b128 v[4:7], v102 offset:32256
	s_waitcnt lgkmcnt(0)
	v_mfma_f32_16x16x32_bf16 v[4:7], v[4:7], v[70:73], 0
	v_mfma_f32_16x16x32_bf16 v[4:7], v[108:111], v[0:3], v[4:7]
	ds_read_b128 v[108:111], v106
	s_waitcnt lgkmcnt(0)
	v_mfma_f32_16x16x32_bf16 v[70:73], v[108:111], v[70:73], 0
	ds_read_b128 v[108:111], v106 offset:64
	s_waitcnt lgkmcnt(0)
; DI f32x4 mfma16(bf16x8 a, bf16x8 b, f32x4 c) { return __builtin_amdgcn_mfma_f32_16x16x32_bf16(a, b, c, 0, 0, 0); }
; DI void mem_attn_item(ldsp lds, const bf16_t* proj, int ldp, int qmcol, int gatecol, const bf16_t* kv, bf16_t* branch, int b0, int item, int tid, int wid, int lane, const bool stage = true) {
;     ...
;     for (int t = 0; t < 16; ++t) {
;         sacc[t] = (f32x4){0.f, 0.f, 0.f, 0.f};
;         const ldsp ka = Kb + (16 * t + li) * KS + quad * 16;
; #pragma unroll
;         for (int ks = 0; ks < 2; ++ks) sacc[t] = mfma16(lds_rd8(ka + ks * 64), qf[ks], sacc[t]);
;     }
;     float mx = -INFINITY;
; #pragma unroll
;     for (int t = 0; t < 16; ++t)
; #pragma unroll
;         for (int j = 0; j < 4; ++j) { const float v = sacc[t][j] * 0.125f; sacc[t][j] = v; mx = fmaxf(mx, v); }
;     mx = fmaxf(mx, __shfl_xor(mx, 16)); mx = fmaxf(mx, __shfl_xor(mx, 32));
	v_mfma_f32_16x16x32_bf16 v[0:3], v[108:111], v[0:3], v[70:73]
	s_nop 4
	v_mul_f32_e32 v70, 0x3e000000, v66
	v_mul_f32_e32 v71, 0x3e000000, v67
	v_max3_f32 v70, v70, s15, v71
	v_mul_f32_e32 v71, 0x3e000000, v68
	v_mul_f32_e32 v72, 0x3e000000, v69
	v_max3_f32 v70, v70, v71, v72
	v_mul_f32_e32 v71, 0x3e000000, v62
	v_mul_f32_e32 v72, 0x3e000000, v63
	v_max3_f32 v70, v70, v71, v72
	v_mul_f32_e32 v71, 0x3e000000, v64
	v_mul_f32_e32 v72, 0x3e000000, v65
	v_max3_f32 v70, v70, v71, v72
	v_mul_f32_e32 v71, 0x3e000000, v58
	v_mul_f32_e32 v72, 0x3e000000, v59
	v_max3_f32 v70, v70, v71, v72
	v_mul_f32_e32 v71, 0x3e000000, v60
	v_mul_f32_e32 v72, 0x3e000000, v61
	v_max3_f32 v70, v70, v71, v72
	v_mul_f32_e32 v71, 0x3e000000, v54
	v_mul_f32_e32 v72, 0x3e000000, v55
	v_max3_f32 v70, v70, v71, v72
	v_mul_f32_e32 v71, 0x3e000000, v56
	v_mul_f32_e32 v72, 0x3e000000, v57
	v_max3_f32 v70, v70, v71, v72
	v_mul_f32_e32 v71, 0x3e000000, v50
	v_mul_f32_e32 v72, 0x3e000000, v51
	v_max3_f32 v70, v70, v71, v72
	v_mul_f32_e32 v71, 0x3e000000, v52
	v_mul_f32_e32 v72, 0x3e000000, v53
	v_max3_f32 v70, v70, v71, v72
	v_mul_f32_e32 v71, 0x3e000000, v46
	v_mul_f32_e32 v72, 0x3e000000, v47
	v_max3_f32 v70, v70, v71, v72
	v_mul_f32_e32 v71, 0x3e000000, v48
	v_mul_f32_e32 v72, 0x3e000000, v49
	v_max3_f32 v70, v70, v71, v72
	v_mul_f32_e32 v71, 0x3e000000, v42
	v_mul_f32_e32 v72, 0x3e000000, v43
	v_max3_f32 v70, v70, v71, v72
	v_mul_f32_e32 v71, 0x3e000000, v44
	v_mul_f32_e32 v72, 0x3e000000, v45
	v_max3_f32 v70, v70, v71, v72
	v_mul_f32_e32 v71, 0x3e000000, v38
	v_mul_f32_e32 v72, 0x3e000000, v39
	v_max3_f32 v70, v70, v71, v72
	v_mul_f32_e32 v71, 0x3e000000, v40
	v_mul_f32_e32 v72, 0x3e000000, v41
	v_max3_f32 v70, v70, v71, v72
	v_mul_f32_e32 v71, 0x3e000000, v34
	v_mul_f32_e32 v72, 0x3e000000, v35
	v_max3_f32 v70, v70, v71, v72
	v_mul_f32_e32 v71, 0x3e000000, v36
	v_mul_f32_e32 v72, 0x3e000000, v37
	v_max3_f32 v70, v70, v71, v72
	v_mul_f32_e32 v71, 0x3e000000, v26
	v_mul_f32_e32 v72, 0x3e000000, v27
	v_max3_f32 v70, v70, v71, v72
	v_mul_f32_e32 v71, 0x3e000000, v28
	v_mul_f32_e32 v72, 0x3e000000, v29
	v_max3_f32 v70, v70, v71, v72
	v_mul_f32_e32 v71, 0x3e000000, v22
	v_mul_f32_e32 v72, 0x3e000000, v23
	v_max3_f32 v70, v70, v71, v72
	v_mul_f32_e32 v71, 0x3e000000, v24
	v_mul_f32_e32 v72, 0x3e000000, v25
	v_max3_f32 v70, v70, v71, v72
	v_mul_f32_e32 v71, 0x3e000000, v14
	v_mul_f32_e32 v72, 0x3e000000, v15
	v_max3_f32 v70, v70, v71, v72
	v_mul_f32_e32 v71, 0x3e000000, v16
	v_mul_f32_e32 v72, 0x3e000000, v17
	v_max3_f32 v70, v70, v71, v72
	v_mul_f32_e32 v71, 0x3e000000, v18
	v_mul_f32_e32 v72, 0x3e000000, v19
	v_max3_f32 v70, v70, v71, v72
	v_mul_f32_e32 v71, 0x3e000000, v20
	v_mul_f32_e32 v72, 0x3e000000, v21
	v_max3_f32 v70, v70, v71, v72
	v_mul_f32_e32 v71, 0x3e000000, v8
	v_mul_f32_e32 v72, 0x3e000000, v9
	v_max3_f32 v70, v70, v71, v72
	v_mul_f32_e32 v71, 0x3e000000, v10
	v_mul_f32_e32 v72, 0x3e000000, v11
	v_max3_f32 v70, v70, v71, v72
	v_mul_f32_e32 v71, 0x3e000000, v4
	v_mul_f32_e32 v72, 0x3e000000, v5
	v_max3_f32 v70, v70, v71, v72
	v_mul_f32_e32 v71, 0x3e000000, v6
	v_mul_f32_e32 v72, 0x3e000000, v7
	v_max3_f32 v70, v70, v71, v72
	v_mul_f32_e32 v71, 0x3e000000, v0
	v_mul_f32_e32 v72, 0x3e000000, v1
	v_max3_f32 v70, v70, v71, v72
	v_mul_f32_e32 v71, 0x3e000000, v2
	v_mul_f32_e32 v72, 0x3e000000, v3
	v_max3_f32 v70, v70, v71, v72
	ds_bpermute_b32 v71, v33, v70
	v_min3_f32 v224, v66, v67, v68
	v_min3_f32 v224, v224, v69, v62
	v_min3_f32 v224, v224, v63, v64
	v_min3_f32 v224, v224, v65, v58
	v_min3_f32 v224, v224, v59, v60
	v_min3_f32 v224, v224, v61, v54
	v_min3_f32 v224, v224, v55, v56
	v_min3_f32 v224, v224, v57, v50
	v_min3_f32 v224, v224, v51, v52
	v_min3_f32 v224, v224, v53, v46
	v_min3_f32 v224, v224, v47, v48
	v_min3_f32 v224, v224, v49, v42
	v_min3_f32 v224, v224, v43, v44
	v_min3_f32 v224, v224, v45, v38
	v_min3_f32 v224, v224, v39, v40
	v_min3_f32 v224, v224, v41, v34
	s_waitcnt lgkmcnt(0)
	v_max_f32_e32 v71, v71, v71
	v_max_f32_e32 v70, v70, v71
	ds_bpermute_b32 v71, v96, v70
	v_min3_f32 v224, v224, v35, v36
	v_min3_f32 v224, v224, v37, v26
	v_min3_f32 v224, v224, v27, v28
	v_min3_f32 v224, v224, v29, v22
	v_min3_f32 v224, v224, v23, v24
	v_min3_f32 v224, v224, v25, v14
	v_min3_f32 v224, v224, v15, v16
	v_min3_f32 v224, v224, v17, v18
	v_min3_f32 v224, v224, v19, v20
	v_min3_f32 v224, v224, v21, v8
	v_min3_f32 v224, v224, v9, v10
	v_min3_f32 v224, v224, v11, v4
	v_min3_f32 v224, v224, v5, v6
	v_min3_f32 v224, v224, v7, v0
	v_min3_f32 v224, v224, v1, v2
	v_min_f32_e32 v224, v224, v3
	s_waitcnt lgkmcnt(0)
	v_max_f32_e32 v71, v71, v71
	v_max_f32_e32 v85, v70, v71
	v_fma_f32 v225, v224, s85, -v85
	v_mul_f32_e32 v225, 0x3fb8aa3b, v225
	v_cmp_gt_f32_e32 vcc, s86, v225
	s_cbranch_vccnz .Lma_slow_dil
; DI unsigned cvt_pk_bf16(float lo, float hi) { const f32x2_t v = {lo, hi}; const bf16v2_t b = __builtin_convertvector(v, bf16v2_t); return __builtin_bit_cast(unsigned, b); }
; DI f32x4 mfma16(bf16x8 a, bf16x8 b, f32x4 c) { return __builtin_amdgcn_mfma_f32_16x16x32_bf16(a, b, c, 0, 0, 0); }
; DI void mem_attn_item(ldsp lds, const bf16_t* proj, int ldp, int qmcol, int gatecol, const bf16_t* kv, bf16_t* branch, int b0, int item, int tid, int wid, int lane, const bool stage = true) {
;     ...
;     float den = 0.f;
; #pragma unroll
;     for (int t = 0; t < 16; ++t)
; #pragma unroll
;         for (int j = 0; j < 4; ++j) { const float pv = exp2f((sacc[t][j] - mx) * 1.4426950408889634f); sacc[t][j] = pv; den += pv; }
;     den += __shfl_xor(den, 16); den += __shfl_xor(den, 32);
;     f32x4 oacc[4];
; #pragma unroll
;     for (int dt = 0; dt < 4; ++dt) oacc[dt] = (f32x4){0.f, 0.f, 0.f, 0.f};
; #pragma unroll
;     for (int kt = 0; kt < 8; ++kt) {
;         u32x4 pw; pw.x = cvt_pk_bf16(sacc[2 * kt][0], sacc[2 * kt][1]); pw.y = cvt_pk_bf16(sacc[2 * kt][2], sacc[2 * kt][3]);
;         pw.z = cvt_pk_bf16(sacc[2 * kt + 1][0], sacc[2 * kt + 1][1]); pw.w = cvt_pk_bf16(sacc[2 * kt + 1][2], sacc[2 * kt + 1][3]);
;         const bf16x8 pf = __builtin_bit_cast(bf16x8, pw);
;         const ldsp va = Vb + (32 * kt + quad * 4 + (li >> 2)) * KS + (li & 3) * 8;
; #pragma unroll
;         for (int dt = 0; dt < 4; ++dt) oacc[dt] = mfma16(lds_tr8(va + dt * 32, va + 16 * KS + dt * 32), pf, oacc[dt]);
;     }
	v_fma_f32 v66, v66, s85, -v85
	v_mul_f32_e32 v70, 0x3fb8aa3b, v66
	v_fma_f32 v67, v67, s85, -v85
	v_fma_f32 v68, v68, s85, -v85
	v_exp_f32_e32 v66, v70
	v_mul_f32_e32 v71, 0x3fb8aa3b, v68
	v_fma_f32 v69, v69, s85, -v85
	v_mul_f32_e32 v70, 0x3fb8aa3b, v67
	v_fma_f32 v62, v62, s85, -v85
	v_fma_f32 v63, v63, s85, -v85
	v_exp_f32_e32 v67, v70
	v_fma_f32 v58, v58, s85, -v85
	v_exp_f32_e32 v68, v71
	v_add_f32_e32 v70, v66, v67
	v_fma_f32 v59, v59, s85, -v85
	v_mul_f32_e32 v71, 0x3fb8aa3b, v69
	v_add_f32_e32 v70, v68, v70
	v_fma_f32 v60, v60, s85, -v85
	v_exp_f32_e32 v69, v71
	v_fma_f32 v61, v61, s85, -v85
	v_fma_f32 v54, v54, s85, -v85
	v_add_f32_e32 v71, v69, v70
	v_mul_f32_e32 v70, 0x3fb8aa3b, v62
	v_fma_f32 v55, v55, s85, -v85
	v_fma_f32 v56, v56, s85, -v85
	v_exp_f32_e32 v62, v70
	v_fma_f32 v57, v57, s85, -v85
	v_fma_f32 v50, v50, s85, -v85
	v_mov_b32_e32 v70, v62
	v_add_f32_e32 v62, v70, v71
	v_mul_f32_e32 v71, 0x3fb8aa3b, v63
	v_fma_f32 v51, v51, s85, -v85
	v_fma_f32 v52, v52, s85, -v85
	v_exp_f32_e32 v63, v71
	v_fma_f32 v53, v53, s85, -v85
	v_fma_f32 v46, v46, s85, -v85
	v_mov_b32_e32 v71, v63
	v_fma_f32 v63, v64, s85, -v85
	v_mul_f32_e32 v64, 0x3fb8aa3b, v63
	v_fma_f32 v47, v47, s85, -v85
	v_fma_f32 v48, v48, s85, -v85
	v_exp_f32_e32 v63, v64
	v_fma_f32 v49, v49, s85, -v85
	v_fma_f32 v42, v42, s85, -v85
	v_mov_b32_e32 v72, v63
	v_fma_f32 v63, v65, s85, -v85
	v_mul_f32_e32 v64, 0x3fb8aa3b, v63
	v_fma_f32 v43, v43, s85, -v85
	v_fma_f32 v44, v44, s85, -v85
	v_exp_f32_e32 v63, v64
	v_fma_f32 v45, v45, s85, -v85
	v_fma_f32 v38, v38, s85, -v85
	v_mov_b32_e32 v73, v63
	v_mul_f32_e32 v63, 0x3fb8aa3b, v58
	v_fma_f32 v39, v39, s85, -v85
	v_fma_f32 v40, v40, s85, -v85
	v_exp_f32_e32 v58, v63
	v_fma_f32 v41, v41, s85, -v85
	v_fma_f32 v34, v34, s85, -v85
	v_mul_f32_e32 v63, 0x3fb8aa3b, v59
	v_fma_f32 v35, v35, s85, -v85
	v_fma_f32 v36, v36, s85, -v85
	v_exp_f32_e32 v59, v63
	v_add_f32_e32 v62, v71, v62
	v_add_f32_e32 v62, v72, v62
	v_mul_f32_e32 v63, 0x3fb8aa3b, v60
	v_add_f32_e32 v62, v73, v62
	v_add_f32_e32 v62, v58, v62
	v_exp_f32_e32 v60, v63
	v_add_f32_e32 v62, v59, v62
	v_fma_f32 v37, v37, s85, -v85
	v_mul_f32_e32 v63, 0x3fb8aa3b, v61
	v_add_f32_e32 v62, v60, v62
	v_fma_f32 v26, v26, s85, -v85
	v_exp_f32_e32 v61, v63
	v_fma_f32 v27, v27, s85, -v85
	v_fma_f32 v28, v28, s85, -v85
	v_mul_f32_e32 v63, 0x3fb8aa3b, v54
	v_add_f32_e32 v62, v61, v62
	v_fma_f32 v29, v29, s85, -v85
	v_exp_f32_e32 v54, v63
	v_fma_f32 v22, v22, s85, -v85
	v_fma_f32 v23, v23, s85, -v85
	v_mul_f32_e32 v63, 0x3fb8aa3b, v55
	v_add_f32_e32 v62, v54, v62
	v_fma_f32 v24, v24, s85, -v85
	v_exp_f32_e32 v55, v63
	v_fma_f32 v25, v25, s85, -v85
	v_fma_f32 v14, v14, s85, -v85
	v_mul_f32_e32 v63, 0x3fb8aa3b, v56
	v_add_f32_e32 v62, v55, v62
	v_fma_f32 v15, v15, s85, -v85
	v_exp_f32_e32 v56, v63
	v_fma_f32 v8, v8, s85, -v85
	v_fma_f32 v9, v9, s85, -v85
	v_mul_f32_e32 v63, 0x3fb8aa3b, v57
	v_add_f32_e32 v62, v56, v62
	v_cvt_pk_bf16_f32 v66, v66, v67
	v_exp_f32_e32 v57, v63
	v_cvt_pk_bf16_f32 v67, v68, v69
	v_cvt_pk_bf16_f32 v68, v70, v71
	v_mul_f32_e32 v63, 0x3fb8aa3b, v50
	v_add_f32_e32 v62, v57, v62
	v_cvt_pk_bf16_f32 v69, v72, v73
	v_exp_f32_e32 v50, v63
	ds_read_b64_tr_b16 v[72:73], v97 offset:39168
	ds_read_b64_tr_b16 v[70:71], v97 offset:36864
	ds_read_b64_tr_b16 v[108:109], v97 offset:36896
	ds_read_b64_tr_b16 v[110:111], v97 offset:39200
	v_mul_f32_e32 v63, 0x3fb8aa3b, v51
	v_add_f32_e32 v62, v50, v62
	ds_read_b64_tr_b16 v[112:113], v97 offset:36928
	ds_read_b64_tr_b16 v[114:115], v97 offset:39232
	v_exp_f32_e32 v51, v63
	ds_read_b64_tr_b16 v[116:117], v97 offset:36960
	ds_read_b64_tr_b16 v[118:119], v97 offset:39264
	v_cvt_pk_bf16_f32 v58, v58, v59
	v_mul_f32_e32 v63, 0x3fb8aa3b, v52
	v_add_f32_e32 v62, v51, v62
	v_cvt_pk_bf16_f32 v59, v60, v61
	v_exp_f32_e32 v52, v63
	v_cvt_pk_bf16_f32 v60, v54, v55
	v_cvt_pk_bf16_f32 v61, v56, v57
	v_mul_f32_e32 v63, 0x3fb8aa3b, v53
	v_add_f32_e32 v62, v52, v62
	ds_read_b64_tr_b16 v[54:55], v97 offset:41472
	ds_read_b64_tr_b16 v[56:57], v97 offset:43776
	v_exp_f32_e32 v53, v63
	v_fma_f32 v10, v10, s85, -v85
	s_waitcnt lgkmcnt(8)
	v_mfma_f32_16x16x32_bf16 v[70:73], v[70:73], v[66:69], 0
	v_mul_f32_e32 v63, 0x3fb8aa3b, v46
	v_add_f32_e32 v62, v53, v62
	s_waitcnt lgkmcnt(0)
	v_mfma_f32_16x16x32_bf16 v[54:57], v[54:57], v[58:61], v[70:73]
	v_exp_f32_e32 v46, v63
	s_nop 2
	ds_read_b64_tr_b16 v[70:71], v97 offset:41504
	ds_read_b64_tr_b16 v[72:73], v97 offset:43808
	v_mfma_f32_16x16x32_bf16 v[108:111], v[108:111], v[66:69], 0
	v_mul_f32_e32 v63, 0x3fb8aa3b, v47
	v_add_f32_e32 v62, v46, v62
	v_fma_f32 v11, v11, s85, -v85
	v_exp_f32_e32 v47, v63
	s_waitcnt lgkmcnt(0)
	v_mfma_f32_16x16x32_bf16 v[70:73], v[70:73], v[58:61], v[108:111]
	s_nop 2
	ds_read_b64_tr_b16 v[108:109], v97 offset:41536
	ds_read_b64_tr_b16 v[110:111], v97 offset:43840
	v_mul_f32_e32 v63, 0x3fb8aa3b, v48
	v_add_f32_e32 v62, v47, v62
	v_mfma_f32_16x16x32_bf16 v[112:115], v[112:115], v[66:69], 0
	v_exp_f32_e32 v48, v63
	s_waitcnt lgkmcnt(0)
	v_mfma_f32_16x16x32_bf16 v[108:111], v[108:111], v[58:61], v[112:115]
	s_nop 2
	s_nop 1
	ds_read_b64_tr_b16 v[112:113], v97 offset:41568
	ds_read_b64_tr_b16 v[114:115], v97 offset:43872
	v_mul_f32_e32 v63, 0x3fb8aa3b, v49
	v_add_f32_e32 v62, v48, v62
	v_cvt_pk_bf16_f32 v50, v50, v51
	v_exp_f32_e32 v49, v63
	v_cvt_pk_bf16_f32 v51, v52, v53
	v_cvt_pk_bf16_f32 v52, v46, v47
	v_mul_f32_e32 v63, 0x3fb8aa3b, v42
	v_add_f32_e32 v62, v49, v62
	v_cvt_pk_bf16_f32 v53, v48, v49
	v_exp_f32_e32 v42, v63
	ds_read_b64_tr_b16 v[46:47], v97 offset:46080
	ds_read_b64_tr_b16 v[48:49], v97 offset:48384
	v_fma_f32 v4, v4, s85, -v85
	v_mul_f32_e32 v63, 0x3fb8aa3b, v43
	v_add_f32_e32 v62, v42, v62
	s_waitcnt lgkmcnt(0)
; DI unsigned cvt_pk_bf16(float lo, float hi) { const f32x2_t v = {lo, hi}; const bf16v2_t b = __builtin_convertvector(v, bf16v2_t); return __builtin_bit_cast(unsigned, b); }
; DI f32x4 mfma16(bf16x8 a, bf16x8 b, f32x4 c) { return __builtin_amdgcn_mfma_f32_16x16x32_bf16(a, b, c, 0, 0, 0); }
; DI void mem_attn_item(ldsp lds, const bf16_t* proj, int ldp, int qmcol, int gatecol, const bf16_t* kv, bf16_t* branch, int b0, int item, int tid, int wid, int lane, const bool stage = true) {
;     ...
;     float den = 0.f;
; #pragma unroll
;     for (int t = 0; t < 16; ++t)
; #pragma unroll
;         for (int j = 0; j < 4; ++j) { const float pv = exp2f((sacc[t][j] - mx) * 1.4426950408889634f); sacc[t][j] = pv; den += pv; }
;     den += __shfl_xor(den, 16); den += __shfl_xor(den, 32);
;     f32x4 oacc[4];
; #pragma unroll
;     for (int dt = 0; dt < 4; ++dt) oacc[dt] = (f32x4){0.f, 0.f, 0.f, 0.f};
; #pragma unroll
;     for (int kt = 0; kt < 8; ++kt) {
;         u32x4 pw; pw.x = cvt_pk_bf16(sacc[2 * kt][0], sacc[2 * kt][1]); pw.y = cvt_pk_bf16(sacc[2 * kt][2], sacc[2 * kt][3]);
;         pw.z = cvt_pk_bf16(sacc[2 * kt + 1][0], sacc[2 * kt + 1][1]); pw.w = cvt_pk_bf16(sacc[2 * kt + 1][2], sacc[2 * kt + 1][3]);
;         const bf16x8 pf = __builtin_bit_cast(bf16x8, pw);
;         const ldsp va = Vb + (32 * kt + quad * 4 + (li >> 2)) * KS + (li & 3) * 8;
; #pragma unroll
;         for (int dt = 0; dt < 4; ++dt) oacc[dt] = mfma16(lds_tr8(va + dt * 32, va + 16 * KS + dt * 32), pf, oacc[dt]);
;     }
	v_mfma_f32_16x16x32_bf16 v[46:49], v[46:49], v[50:53], v[54:57]
	v_exp_f32_e32 v43, v63
	s_nop 1
	ds_read_b64_tr_b16 v[54:55], v97 offset:46112
	ds_read_b64_tr_b16 v[56:57], v97 offset:48416
	v_mfma_f32_16x16x32_bf16 v[66:69], v[116:119], v[66:69], 0
	v_mul_f32_e32 v63, 0x3fb8aa3b, v44
	v_add_f32_e32 v62, v43, v62
	v_fma_f32 v5, v5, s85, -v85
	v_exp_f32_e32 v44, v63
	v_mfma_f32_16x16x32_bf16 v[58:61], v[112:115], v[58:61], v[66:69]
	s_nop 2
	ds_read_b64_tr_b16 v[66:67], v97 offset:46144
	ds_read_b64_tr_b16 v[68:69], v97 offset:48448
	v_mul_f32_e32 v63, 0x3fb8aa3b, v45
	v_add_f32_e32 v62, v44, v62
	s_waitcnt lgkmcnt(2)
	v_mfma_f32_16x16x32_bf16 v[54:57], v[54:57], v[50:53], v[70:73]
	v_exp_f32_e32 v45, v63
	s_nop 1
	ds_read_b64_tr_b16 v[70:71], v97 offset:46176
	ds_read_b64_tr_b16 v[72:73], v97 offset:48480
	v_cvt_pk_bf16_f32 v42, v42, v43
	v_mul_f32_e32 v63, 0x3fb8aa3b, v38
	v_add_f32_e32 v62, v45, v62
	v_cvt_pk_bf16_f32 v43, v44, v45
	v_exp_f32_e32 v38, v63
	v_fma_f32 v6, v6, s85, -v85
	s_waitcnt lgkmcnt(2)
	v_mfma_f32_16x16x32_bf16 v[66:69], v[66:69], v[50:53], v[108:111]
	v_mul_f32_e32 v63, 0x3fb8aa3b, v39
	v_add_f32_e32 v62, v38, v62
	s_waitcnt lgkmcnt(0)
	v_mfma_f32_16x16x32_bf16 v[50:53], v[70:73], v[50:53], v[58:61]
	v_exp_f32_e32 v39, v63
	v_fma_f32 v7, v7, s85, -v85
	v_fma_f32 v0, v0, s85, -v85
	v_mul_f32_e32 v63, 0x3fb8aa3b, v40
	v_add_f32_e32 v62, v39, v62
	v_cvt_pk_bf16_f32 v44, v38, v39
	v_exp_f32_e32 v40, v63
	v_fma_f32 v1, v1, s85, -v85
	v_fma_f32 v2, v2, s85, -v85
	v_mul_f32_e32 v63, 0x3fb8aa3b, v41
	v_add_f32_e32 v62, v40, v62
	v_fma_f32 v3, v3, s85, -v85
	v_exp_f32_e32 v41, v63
	v_mul_f32_e32 v63, 0x3fb8aa3b, v34
	v_add_f32_e32 v62, v41, v62
	v_cvt_pk_bf16_f32 v45, v40, v41
	v_exp_f32_e32 v34, v63
	ds_read_b64_tr_b16 v[38:39], v97 offset:50688
	ds_read_b64_tr_b16 v[40:41], v97 offset:52992
	s_waitcnt lgkmcnt(0)
	v_mfma_f32_16x16x32_bf16 v[38:41], v[38:41], v[42:45], v[46:49]
	v_mul_f32_e32 v63, 0x3fb8aa3b, v35
	v_add_f32_e32 v62, v34, v62
	s_nop 0
	ds_read_b64_tr_b16 v[46:47], v97 offset:50720
	ds_read_b64_tr_b16 v[48:49], v97 offset:53024
	v_exp_f32_e32 v35, v63
	s_waitcnt lgkmcnt(0)
	v_mfma_f32_16x16x32_bf16 v[46:49], v[46:49], v[42:45], v[54:57]
	s_nop 2
	ds_read_b64_tr_b16 v[54:55], v97 offset:50752
	ds_read_b64_tr_b16 v[56:57], v97 offset:53056
	v_mul_f32_e32 v63, 0x3fb8aa3b, v36
	v_add_f32_e32 v62, v35, v62
	ds_read_b64_tr_b16 v[58:59], v97 offset:50784
	ds_read_b64_tr_b16 v[60:61], v97 offset:53088
	v_exp_f32_e32 v36, v63
	s_waitcnt lgkmcnt(2)
	v_mfma_f32_16x16x32_bf16 v[54:57], v[54:57], v[42:45], v[66:69]
	v_cvt_pk_bf16_f32 v34, v34, v35
	v_mul_f32_e32 v63, 0x3fb8aa3b, v37
	v_add_f32_e32 v62, v36, v62
	s_waitcnt lgkmcnt(0)
	v_mfma_f32_16x16x32_bf16 v[42:45], v[58:61], v[42:45], v[50:53]
	v_exp_f32_e32 v37, v63
	s_nop 1
	ds_read_b64_tr_b16 v[50:51], v97 offset:55296
	ds_read_b64_tr_b16 v[52:53], v97 offset:57600
	v_mul_f32_e32 v63, 0x3fb8aa3b, v26
	v_add_f32_e32 v62, v37, v62
	v_cvt_pk_bf16_f32 v35, v36, v37
	v_exp_f32_e32 v26, v63
	v_mul_f32_e32 v63, 0x3fb8aa3b, v27
	v_add_f32_e32 v62, v26, v62
	s_nop 0
	v_exp_f32_e32 v27, v63
	s_nop 0
	v_add_f32_e32 v63, v27, v62
	v_mul_f32_e32 v62, 0x3fb8aa3b, v28
	v_cvt_pk_bf16_f32 v36, v26, v27
	s_nop 0
	v_exp_f32_e32 v28, v62
	s_nop 0
	v_mov_b32_e32 v62, v28
	v_add_f32_e32 v28, v62, v63
	v_mul_f32_e32 v63, 0x3fb8aa3b, v29
	s_nop 1
	v_exp_f32_e32 v29, v63
	s_nop 0
	v_mov_b32_e32 v63, v29
	v_mul_f32_e32 v29, 0x3fb8aa3b, v22
	v_add_f32_e32 v28, v63, v28
	v_cvt_pk_bf16_f32 v37, v62, v63
	v_exp_f32_e32 v22, v29
	s_waitcnt lgkmcnt(0)
	v_mfma_f32_16x16x32_bf16 v[38:41], v[50:53], v[34:37], v[38:41]
	ds_read_b64_tr_b16 v[50:51], v97 offset:55328
	ds_read_b64_tr_b16 v[52:53], v97 offset:57632
	v_mul_f32_e32 v29, 0x3fb8aa3b, v23
	v_add_f32_e32 v28, v22, v28
	s_waitcnt lgkmcnt(0)
	v_mfma_f32_16x16x32_bf16 v[46:49], v[50:53], v[34:37], v[46:49]
	v_exp_f32_e32 v23, v29
	ds_read_b64_tr_b16 v[50:51], v97 offset:55360
	ds_read_b64_tr_b16 v[52:53], v97 offset:57664
	s_waitcnt lgkmcnt(0)
	v_mfma_f32_16x16x32_bf16 v[50:53], v[50:53], v[34:37], v[54:57]
	v_mul_f32_e32 v29, 0x3fb8aa3b, v24
	v_add_f32_e32 v28, v23, v28
	s_nop 0
	ds_read_b64_tr_b16 v[54:55], v97 offset:55392
	ds_read_b64_tr_b16 v[56:57], v97 offset:57696
	v_exp_f32_e32 v24, v29
	s_waitcnt lgkmcnt(0)
; DI unsigned cvt_pk_bf16(float lo, float hi) { const f32x2_t v = {lo, hi}; const bf16v2_t b = __builtin_convertvector(v, bf16v2_t); return __builtin_bit_cast(unsigned, b); }
; DI f32x4 mfma16(bf16x8 a, bf16x8 b, f32x4 c) { return __builtin_amdgcn_mfma_f32_16x16x32_bf16(a, b, c, 0, 0, 0); }
; DI void mem_attn_item(ldsp lds, const bf16_t* proj, int ldp, int qmcol, int gatecol, const bf16_t* kv, bf16_t* branch, int b0, int item, int tid, int wid, int lane, const bool stage = true) {
;     ...
;     float den = 0.f;
; #pragma unroll
;     for (int t = 0; t < 16; ++t)
; #pragma unroll
;         for (int j = 0; j < 4; ++j) { const float pv = exp2f((sacc[t][j] - mx) * 1.4426950408889634f); sacc[t][j] = pv; den += pv; }
;     den += __shfl_xor(den, 16); den += __shfl_xor(den, 32);
;     f32x4 oacc[4];
; #pragma unroll
;     for (int dt = 0; dt < 4; ++dt) oacc[dt] = (f32x4){0.f, 0.f, 0.f, 0.f};
; #pragma unroll
;     for (int kt = 0; kt < 8; ++kt) {
;         u32x4 pw; pw.x = cvt_pk_bf16(sacc[2 * kt][0], sacc[2 * kt][1]); pw.y = cvt_pk_bf16(sacc[2 * kt][2], sacc[2 * kt][3]);
;         pw.z = cvt_pk_bf16(sacc[2 * kt + 1][0], sacc[2 * kt + 1][1]); pw.w = cvt_pk_bf16(sacc[2 * kt + 1][2], sacc[2 * kt + 1][3]);
;         const bf16x8 pf = __builtin_bit_cast(bf16x8, pw);
;         const ldsp va = Vb + (32 * kt + quad * 4 + (li >> 2)) * KS + (li & 3) * 8;
; #pragma unroll
;         for (int dt = 0; dt < 4; ++dt) oacc[dt] = mfma16(lds_tr8(va + dt * 32, va + 16 * KS + dt * 32), pf, oacc[dt]);
;     }
	v_mfma_f32_16x16x32_bf16 v[34:37], v[54:57], v[34:37], v[42:45]
	v_mul_f32_e32 v29, 0x3fb8aa3b, v25
	v_add_f32_e32 v28, v24, v28
	s_nop 0
	v_exp_f32_e32 v25, v29
	s_nop 0
	v_add_f32_e32 v29, v25, v28
	v_mul_f32_e32 v28, 0x3fb8aa3b, v14
	s_nop 1
	v_exp_f32_e32 v14, v28
	s_nop 0
	v_mov_b32_e32 v28, v14
	v_add_f32_e32 v14, v28, v29
	v_mul_f32_e32 v29, 0x3fb8aa3b, v15
	s_nop 1
	v_exp_f32_e32 v15, v29
	s_nop 0
	v_mov_b32_e32 v29, v15
	v_fma_f32 v15, v16, s85, -v85
	v_mul_f32_e32 v16, 0x3fb8aa3b, v15
	v_add_f32_e32 v14, v29, v14
	s_nop 0
	v_exp_f32_e32 v15, v16
	s_nop 0
	v_mov_b32_e32 v64, v15
	v_fma_f32 v15, v17, s85, -v85
	v_mul_f32_e32 v16, 0x3fb8aa3b, v15
	v_add_f32_e32 v14, v64, v14
	s_nop 0
	v_exp_f32_e32 v15, v16
	s_nop 0
	v_mov_b32_e32 v65, v15
	v_add_f32_e32 v15, v65, v14
	v_fma_f32 v14, v18, s85, -v85
	v_mul_f32_e32 v16, 0x3fb8aa3b, v14
	s_nop 1
	v_exp_f32_e32 v14, v16
	s_nop 0
	v_add_f32_e32 v16, v14, v15
	v_fma_f32 v15, v19, s85, -v85
	v_mul_f32_e32 v17, 0x3fb8aa3b, v15
	s_nop 1
	v_exp_f32_e32 v15, v17
	s_nop 0
	v_add_f32_e32 v17, v15, v16
	v_fma_f32 v16, v20, s85, -v85
	v_mul_f32_e32 v18, 0x3fb8aa3b, v16
	v_cvt_pk_bf16_f32 v20, v22, v23
	v_cvt_pk_bf16_f32 v22, v28, v29
	v_exp_f32_e32 v16, v18
	v_cvt_pk_bf16_f32 v23, v64, v65
	v_cvt_pk_bf16_f32 v14, v14, v15
	v_add_f32_e32 v18, v16, v17
	v_fma_f32 v17, v21, s85, -v85
	v_mul_f32_e32 v19, 0x3fb8aa3b, v17
	v_cvt_pk_bf16_f32 v21, v24, v25
	ds_read_b64_tr_b16 v[24:25], v97 offset:59904
	ds_read_b64_tr_b16 v[26:27], v97 offset:62208
	v_exp_f32_e32 v17, v19
	s_waitcnt lgkmcnt(0)
	v_mfma_f32_16x16x32_bf16 v[24:27], v[24:27], v[20:23], v[38:41]
	s_nop 2
	ds_read_b64_tr_b16 v[38:39], v97 offset:59936
	ds_read_b64_tr_b16 v[40:41], v97 offset:62240
	v_mul_f32_e32 v19, 0x3fb8aa3b, v8
	v_add_f32_e32 v18, v17, v18
	s_waitcnt lgkmcnt(0)
	v_mfma_f32_16x16x32_bf16 v[38:41], v[38:41], v[20:23], v[46:49]
	v_exp_f32_e32 v8, v19
	ds_read_b64_tr_b16 v[42:43], v97 offset:59968
	ds_read_b64_tr_b16 v[44:45], v97 offset:62272
	ds_read_b64_tr_b16 v[46:47], v97 offset:60000
	ds_read_b64_tr_b16 v[48:49], v97 offset:62304
	v_mul_f32_e32 v19, 0x3fb8aa3b, v9
	v_add_f32_e32 v18, v8, v18
	v_cvt_pk_bf16_f32 v15, v16, v17
	v_exp_f32_e32 v9, v19
	s_waitcnt lgkmcnt(2)
	v_mfma_f32_16x16x32_bf16 v[42:45], v[42:45], v[20:23], v[50:53]
	v_mul_f32_e32 v19, 0x3fb8aa3b, v10
	v_add_f32_e32 v18, v9, v18
	v_cvt_pk_bf16_f32 v16, v8, v9
	v_exp_f32_e32 v10, v19
	s_waitcnt lgkmcnt(0)
	v_mfma_f32_16x16x32_bf16 v[20:23], v[46:49], v[20:23], v[34:37]
	v_mul_f32_e32 v19, 0x3fb8aa3b, v11
	v_add_f32_e32 v18, v10, v18
	s_nop 0
	v_exp_f32_e32 v11, v19
	v_mul_f32_e32 v19, 0x3fb8aa3b, v4
	v_add_f32_e32 v18, v11, v18
	v_cvt_pk_bf16_f32 v17, v10, v11
	v_exp_f32_e32 v4, v19
	ds_read_b64_tr_b16 v[8:9], v97 offset:64512
	ds_read_b64_tr_b16 v[10:11], v98 offset:29952
	ds_read_b64_tr_b16 v[28:29], v98 offset:29984
	s_waitcnt lgkmcnt(1)
	v_mfma_f32_16x16x32_bf16 v[8:11], v[8:11], v[14:17], v[24:27]
	v_mul_f32_e32 v19, 0x3fb8aa3b, v5
	s_nop 1
	ds_read_b64_tr_b16 v[26:27], v97 offset:64544
	v_add_f32_e32 v18, v4, v18
	v_exp_f32_e32 v5, v19
	s_waitcnt lgkmcnt(0)
	v_mfma_f32_16x16x32_bf16 v[24:27], v[26:29], v[14:17], v[38:41]
	v_mul_f32_e32 v19, 0x3fb8aa3b, v6
	v_add_f32_e32 v18, v5, v18
	ds_read_b64_tr_b16 v[34:35], v97 offset:64576
	ds_read_b64_tr_b16 v[36:37], v98 offset:30016
	v_exp_f32_e32 v6, v19
	ds_read_b64_tr_b16 v[38:39], v97 offset:64608
	ds_read_b64_tr_b16 v[40:41], v98 offset:30048
	s_waitcnt lgkmcnt(0)
	v_mfma_f32_16x16x32_bf16 v[20:23], v[38:41], v[14:17], v[20:23]
	v_mul_f32_e32 v19, 0x3fb8aa3b, v7
	v_add_f32_e32 v18, v6, v18
	v_cvt_pk_bf16_f32 v38, v4, v5
	v_exp_f32_e32 v7, v19
	v_mfma_f32_16x16x32_bf16 v[34:37], v[34:37], v[14:17], v[42:45]
	v_mul_f32_e32 v19, 0x3fb8aa3b, v0
	v_add_f32_e32 v18, v7, v18
	v_cvt_pk_bf16_f32 v39, v6, v7
	v_exp_f32_e32 v0, v19
	v_mul_f32_e32 v19, 0x3fb8aa3b, v1
	v_add_f32_e32 v18, v0, v18
	s_nop 0
	v_exp_f32_e32 v1, v19
	v_mul_f32_e32 v19, 0x3fb8aa3b, v2
	v_add_f32_e32 v18, v1, v18
	v_cvt_pk_bf16_f32 v40, v0, v1
	v_exp_f32_e32 v2, v19
	v_mul_f32_e32 v19, 0x3fb8aa3b, v3
	v_add_f32_e32 v18, v2, v18
	s_nop 0
	v_exp_f32_e32 v3, v19
	s_branch .Lma_join_dil

; DI unsigned cvt_pk_bf16(float lo, float hi) { const f32x2_t v = {lo, hi}; const bf16v2_t b = __builtin_convertvector(v, bf16v2_t); return __builtin_bit_cast(unsigned, b); }
; DI float bf_lo(unsigned u) { return __uint_as_float(u << 16); }
; DI float bf_hi(unsigned u) { return __uint_as_float(u & 0xffff0000u); }
; DI f32x4 mfma16(bf16x8 a, bf16x8 b, f32x4 c) { return __builtin_amdgcn_mfma_f32_16x16x32_bf16(a, b, c, 0, 0, 0); }
; DI float silu_f(float x) { return x / (1.0f + __expf(-x)); }
; DI void mem_attn_item(ldsp lds, const bf16_t* proj, int ldp, int qmcol, int gatecol, const bf16_t* kv, bf16_t* branch, int b0, int item, int tid, int wid, int lane, const bool stage = true) {
;     ...
;     den += __shfl_xor(den, 16); den += __shfl_xor(den, 32);
;     f32x4 oacc[4];
; #pragma unroll
;     for (int dt = 0; dt < 4; ++dt) oacc[dt] = (f32x4){0.f, 0.f, 0.f, 0.f};
; #pragma unroll
;     for (int kt = 0; kt < 8; ++kt) {
;         u32x4 pw; pw.x = cvt_pk_bf16(sacc[2 * kt][0], sacc[2 * kt][1]); pw.y = cvt_pk_bf16(sacc[2 * kt][2], sacc[2 * kt][3]);
;         pw.z = cvt_pk_bf16(sacc[2 * kt + 1][0], sacc[2 * kt + 1][1]); pw.w = cvt_pk_bf16(sacc[2 * kt + 1][2], sacc[2 * kt + 1][3]);
;         const bf16x8 pf = __builtin_bit_cast(bf16x8, pw);
;         const ldsp va = Vb + (32 * kt + quad * 4 + (li >> 2)) * KS + (li & 3) * 8;
; #pragma unroll
;         for (int dt = 0; dt < 4; ++dt) oacc[dt] = mfma16(lds_tr8(va + dt * 32, va + 16 * KS + dt * 32), pf, oacc[dt]);
;     }
;     const float inv = 1.0f / den;
;     bf16_t* dst = branch + ((size_t)(b0 + bl) * 2048 + tq) * 1024 + 768 + hm * 64 + quad * 4;
; #pragma unroll
;     for (int dt = 0; dt < 4; ++dt) {
;         const u32x2 gt = gtv[dt];
;         u32x2 o;
;         o.x = cvt_pk_bf16(oacc[dt][0] * inv * silu_f(bf_lo(gt.x)), oacc[dt][1] * inv * silu_f(bf_hi(gt.x)));
;         o.y = cvt_pk_bf16(oacc[dt][2] * inv * silu_f(bf_lo(gt.y)), oacc[dt][3] * inv * silu_f(bf_hi(gt.y)));
;         *(u32x2*)(dst + dt * 16) = o;
;     }
.Lma_join_dil:
	v_add_f32_e32 v18, v3, v18
	v_cvt_pk_bf16_f32 v41, v2, v3
	ds_read_b64_tr_b16 v[0:1], v98 offset:32256
	ds_read_b64_tr_b16 v[2:3], v98 offset:34560
	s_waitcnt lgkmcnt(0)
	v_mfma_f32_16x16x32_bf16 v[14:17], v[0:3], v[38:41], v[8:11]
	ds_read_b64_tr_b16 v[0:1], v98 offset:32288
	ds_read_b64_tr_b16 v[2:3], v98 offset:34592
	ds_bpermute_b32 v19, v33, v18
	s_waitcnt lgkmcnt(0)
	v_add_f32_e32 v18, v18, v19
	v_mfma_f32_16x16x32_bf16 v[8:11], v[0:3], v[38:41], v[24:27]
	ds_read_b64_tr_b16 v[0:1], v98 offset:32320
	ds_read_b64_tr_b16 v[2:3], v98 offset:34624
	ds_bpermute_b32 v19, v96, v18
	s_waitcnt vmcnt(3)
	v_and_b32_e32 v24, 0xffff0000, v92
	s_waitcnt lgkmcnt(1)
	v_mfma_f32_16x16x32_bf16 v[4:7], v[0:3], v[38:41], v[34:37]
	ds_read_b64_tr_b16 v[0:1], v98 offset:32352
	ds_read_b64_tr_b16 v[2:3], v98 offset:34656
	s_waitcnt lgkmcnt(2)
	v_add_f32_e32 v18, v18, v19
	v_div_scale_f32 v19, s[22:23], v18, v18, 1.0
	s_waitcnt lgkmcnt(0)
	v_mfma_f32_16x16x32_bf16 v[0:3], v[0:3], v[38:41], v[20:23]
	s_nop 2
	v_rcp_f32_e32 v20, v19
	s_nop 0
	v_fma_f32 v21, -v19, v20, 1.0
	v_fmac_f32_e32 v20, v21, v20
	v_div_scale_f32 v21, vcc, 1.0, v18, 1.0
	v_mul_f32_e32 v22, v21, v20
	v_fma_f32 v23, -v19, v22, v21
	v_fmac_f32_e32 v22, v23, v20
	v_fma_f32 v19, -v19, v22, v21
	v_lshlrev_b32_e32 v21, 16, v92
	v_div_fmas_f32 v19, v19, v20, v22
	v_mul_f32_e32 v22, 0xbfb8aa3b, v21
	v_mul_f32_e32 v23, 0xbfb8aa3b, v24
	v_exp_f32_e32 v22, v22
	v_exp_f32_e32 v23, v23
	v_div_fixup_f32 v20, v19, v18, 1.0
	v_pk_mul_f32 v[14:15], v[20:21], v[14:15] op_sel_hi:[0,1]
	v_lshlrev_b64 v[18:19], 11, v[94:95]
	v_pk_add_f32 v[22:23], v[22:23], 1.0 op_sel_hi:[1,0]
	v_lshl_add_u64 v[18:19], v[82:83], 0, v[18:19]
	v_div_scale_f32 v25, s[22:23], v23, v23, v24
	v_rcp_f32_e32 v26, v25
	s_nop 0
	v_fma_f32 v27, -v25, v26, 1.0
	v_fmac_f32_e32 v26, v27, v26
	v_div_scale_f32 v27, vcc, v24, v23, v24
	v_mul_f32_e32 v28, v27, v26
	v_fma_f32 v29, -v25, v28, v27
	v_fmac_f32_e32 v28, v29, v26
	v_fma_f32 v25, -v25, v28, v27
	v_div_fmas_f32 v25, v25, v26, v28
	v_div_fixup_f32 v23, v25, v23, v24
	v_div_scale_f32 v24, s[22:23], v22, v22, v21
	v_rcp_f32_e32 v25, v24
	s_nop 0
	v_fma_f32 v26, -v24, v25, 1.0
	v_fmac_f32_e32 v25, v26, v25
	v_div_scale_f32 v26, vcc, v21, v22, v21
	v_mul_f32_e32 v27, v26, v25
	v_fma_f32 v28, -v24, v27, v26
	v_fmac_f32_e32 v27, v28, v25
	v_fma_f32 v24, -v24, v27, v26
	v_div_fmas_f32 v24, v24, v25, v27
	v_div_fixup_f32 v22, v24, v22, v21
	v_pk_mul_f32 v[14:15], v[22:23], v[14:15]
	v_and_b32_e32 v21, 0xffff0000, v93
	v_cvt_pk_bf16_f32 v14, v14, v15
	v_lshlrev_b32_e32 v15, 16, v93
	v_mul_f32_e32 v22, 0xbfb8aa3b, v15
	v_mul_f32_e32 v23, 0xbfb8aa3b, v21
	v_exp_f32_e32 v22, v22
	v_exp_f32_e32 v23, v23
	v_pk_mul_f32 v[16:17], v[20:21], v[16:17] op_sel_hi:[0,1]
	v_pk_add_f32 v[22:23], v[22:23], 1.0 op_sel_hi:[1,0]
	s_nop 0
	v_div_scale_f32 v24, s[22:23], v23, v23, v21
	v_rcp_f32_e32 v25, v24
	s_nop 0
	v_fma_f32 v26, -v24, v25, 1.0
	v_fmac_f32_e32 v25, v26, v25
	v_div_scale_f32 v26, vcc, v21, v23, v21
	v_mul_f32_e32 v27, v26, v25
	v_fma_f32 v28, -v24, v27, v26
	v_fmac_f32_e32 v27, v28, v25
	v_fma_f32 v24, -v24, v27, v26
	v_div_fmas_f32 v24, v24, v25, v27
	v_div_fixup_f32 v23, v24, v23, v21
	v_div_scale_f32 v21, s[22:23], v22, v22, v15
	v_rcp_f32_e32 v24, v21
	s_nop 0
	v_fma_f32 v25, -v21, v24, 1.0
	v_fmac_f32_e32 v24, v25, v24
	v_div_scale_f32 v25, vcc, v15, v22, v15
	v_mul_f32_e32 v26, v25, v24
	v_fma_f32 v27, -v21, v26, v25
	v_fmac_f32_e32 v26, v27, v24
	v_fma_f32 v21, -v21, v26, v25
	v_div_fmas_f32 v21, v21, v24, v26
	v_div_fixup_f32 v22, v21, v22, v15
	v_pk_mul_f32 v[16:17], v[22:23], v[16:17]
	v_pk_mul_f32 v[8:9], v[20:21], v[8:9] op_sel_hi:[0,1]
	v_cvt_pk_bf16_f32 v15, v16, v17
	s_waitcnt vmcnt(2)
	v_lshlrev_b32_e32 v16, 16, v90
	v_and_b32_e32 v17, 0xffff0000, v90
	global_store_dwordx2 v[18:19], v[14:15], off offset:1536
	v_mul_f32_e32 v14, 0xbfb8aa3b, v16
	v_mul_f32_e32 v15, 0xbfb8aa3b, v17
	v_exp_f32_e32 v14, v14
	v_exp_f32_e32 v15, v15
	s_nop 0
	v_pk_add_f32 v[14:15], v[14:15], 1.0 op_sel_hi:[1,0]
	s_nop 0
	v_div_scale_f32 v21, s[22:23], v15, v15, v17
	v_rcp_f32_e32 v22, v21
	s_nop 0
	v_fma_f32 v23, -v21, v22, 1.0
	v_fmac_f32_e32 v22, v23, v22
	v_div_scale_f32 v23, vcc, v17, v15, v17
	v_mul_f32_e32 v24, v23, v22
	v_fma_f32 v25, -v21, v24, v23
	v_fmac_f32_e32 v24, v25, v22
	v_fma_f32 v21, -v21, v24, v23
	v_div_fmas_f32 v21, v21, v22, v24
	v_div_fixup_f32 v15, v21, v15, v17
	v_div_scale_f32 v17, s[22:23], v14, v14, v16
	v_rcp_f32_e32 v21, v17
	s_nop 0
	v_fma_f32 v22, -v17, v21, 1.0
	v_fmac_f32_e32 v21, v22, v21
	v_div_scale_f32 v22, vcc, v16, v14, v16
	v_mul_f32_e32 v23, v22, v21
	v_fma_f32 v24, -v17, v23, v22
	v_fmac_f32_e32 v23, v24, v21
	v_fma_f32 v17, -v17, v23, v22
	v_div_fmas_f32 v17, v17, v21, v23
	v_div_fixup_f32 v14, v17, v14, v16
	v_pk_mul_f32 v[8:9], v[14:15], v[8:9]
	v_and_b32_e32 v16, 0xffff0000, v91
	v_cvt_pk_bf16_f32 v8, v8, v9
	v_lshlrev_b32_e32 v9, 16, v91
	v_mul_f32_e32 v14, 0xbfb8aa3b, v9
	v_mul_f32_e32 v15, 0xbfb8aa3b, v16
	v_exp_f32_e32 v14, v14
	v_exp_f32_e32 v15, v15
	v_pk_mul_f32 v[10:11], v[20:21], v[10:11] op_sel_hi:[0,1]
	v_pk_add_f32 v[14:15], v[14:15], 1.0 op_sel_hi:[1,0]
	s_nop 0
	v_div_scale_f32 v17, s[22:23], v15, v15, v16
	v_rcp_f32_e32 v21, v17
	s_nop 0
	v_fma_f32 v22, -v17, v21, 1.0
	v_fmac_f32_e32 v21, v22, v21
	v_div_scale_f32 v22, vcc, v16, v15, v16
	v_mul_f32_e32 v23, v22, v21
	v_fma_f32 v24, -v17, v23, v22
	v_fmac_f32_e32 v23, v24, v21
	v_fma_f32 v17, -v17, v23, v22
	v_div_fmas_f32 v17, v17, v21, v23
	v_div_fixup_f32 v15, v17, v15, v16
	v_div_scale_f32 v16, s[22:23], v14, v14, v9
	v_rcp_f32_e32 v17, v16
	s_nop 0
	v_fma_f32 v21, -v16, v17, 1.0
	v_fmac_f32_e32 v17, v21, v17
	v_div_scale_f32 v21, vcc, v9, v14, v9
	v_mul_f32_e32 v22, v21, v17
	v_fma_f32 v23, -v16, v22, v21
	v_fmac_f32_e32 v22, v23, v17
	v_fma_f32 v16, -v16, v22, v21
	v_div_fmas_f32 v16, v16, v17, v22
	v_div_fixup_f32 v14, v16, v14, v9
	v_pk_mul_f32 v[10:11], v[14:15], v[10:11]
	v_pk_mul_f32 v[4:5], v[20:21], v[4:5] op_sel_hi:[0,1]
	v_cvt_pk_bf16_f32 v9, v10, v11
	s_waitcnt vmcnt(2)
; #define LAS __attribute__((address_space(3)))
; DI unsigned cvt_pk_bf16(float lo, float hi) { const f32x2_t v = {lo, hi}; const bf16v2_t b = __builtin_convertvector(v, bf16v2_t); return __builtin_bit_cast(unsigned, b); }
; DI float bf_lo(unsigned u) { return __uint_as_float(u << 16); }
; DI float bf_hi(unsigned u) { return __uint_as_float(u & 0xffff0000u); }
; DI float silu_f(float x) { return x / (1.0f + __expf(-x)); }
; DI void mem_attn_item(ldsp lds, const bf16_t* proj, int ldp, int qmcol, int gatecol, const bf16_t* kv, bf16_t* branch, int b0, int item, int tid, int wid, int lane, const bool stage = true) {
;     ...
;     for (int i = 0; i < 4; ++i) {
;         const int e = tid + i * 512, row = e >> 3, ch = e & 7;
;         const u32x4 kx = *(const u32x4*)(kvb + (size_t)row * 2048 + ch * 8);
;         const u32x4 vx = *(const u32x4*)(kvb + (size_t)row * 2048 + 256 + ch * 8);
;         *(LAS u32x4*)(Kb + row * KS + ch * 16) = kx;
;         *(LAS u32x4*)(Vb + row * KS + ch * 16) = vx;
;     }
;     ...
;     const float inv = 1.0f / den;
;     bf16_t* dst = branch + ((size_t)(b0 + bl) * 2048 + tq) * 1024 + 768 + hm * 64 + quad * 4;
; #pragma unroll
;     for (int dt = 0; dt < 4; ++dt) {
;         const u32x2 gt = gtv[dt];
;         u32x2 o;
;         o.x = cvt_pk_bf16(oacc[dt][0] * inv * silu_f(bf_lo(gt.x)), oacc[dt][1] * inv * silu_f(bf_hi(gt.x)));
;         o.y = cvt_pk_bf16(oacc[dt][2] * inv * silu_f(bf_lo(gt.y)), oacc[dt][3] * inv * silu_f(bf_hi(gt.y)));
;         *(u32x2*)(dst + dt * 16) = o;
;     }
;     __syncthreads();
	v_lshlrev_b32_e32 v10, 16, v88
	v_and_b32_e32 v11, 0xffff0000, v88
	global_store_dwordx2 v[18:19], v[8:9], off offset:1568
	v_mul_f32_e32 v8, 0xbfb8aa3b, v10
	v_mul_f32_e32 v9, 0xbfb8aa3b, v11
	v_exp_f32_e32 v8, v8
	v_exp_f32_e32 v9, v9
	s_nop 0
	v_pk_add_f32 v[8:9], v[8:9], 1.0 op_sel_hi:[1,0]
	s_nop 0
	v_div_scale_f32 v14, s[22:23], v9, v9, v11
	v_rcp_f32_e32 v15, v14
	s_nop 0
	v_fma_f32 v16, -v14, v15, 1.0
	v_fmac_f32_e32 v15, v16, v15
	v_div_scale_f32 v16, vcc, v11, v9, v11
	v_mul_f32_e32 v17, v16, v15
	v_fma_f32 v21, -v14, v17, v16
	v_fmac_f32_e32 v17, v21, v15
	v_fma_f32 v14, -v14, v17, v16
	v_div_fmas_f32 v14, v14, v15, v17
	v_div_fixup_f32 v9, v14, v9, v11
	v_div_scale_f32 v11, s[22:23], v8, v8, v10
	v_rcp_f32_e32 v14, v11
	v_pk_mul_f32 v[6:7], v[20:21], v[6:7] op_sel_hi:[0,1]
	v_pk_mul_f32 v[0:1], v[20:21], v[0:1] op_sel_hi:[0,1]
	v_pk_mul_f32 v[2:3], v[20:21], v[2:3] op_sel_hi:[0,1]
	v_fma_f32 v15, -v11, v14, 1.0
	v_fmac_f32_e32 v14, v15, v14
	v_div_scale_f32 v15, vcc, v10, v8, v10
	v_mul_f32_e32 v16, v15, v14
	v_fma_f32 v17, -v11, v16, v15
	v_fmac_f32_e32 v16, v17, v14
	v_fma_f32 v11, -v11, v16, v15
	v_div_fmas_f32 v11, v11, v14, v16
	v_div_fixup_f32 v8, v11, v8, v10
	v_pk_mul_f32 v[4:5], v[8:9], v[4:5]
	v_and_b32_e32 v10, 0xffff0000, v89
	v_cvt_pk_bf16_f32 v4, v4, v5
	v_lshlrev_b32_e32 v5, 16, v89
	v_mul_f32_e32 v8, 0xbfb8aa3b, v5
	v_mul_f32_e32 v9, 0xbfb8aa3b, v10
	v_exp_f32_e32 v8, v8
	v_exp_f32_e32 v9, v9
	s_nop 0
	v_pk_add_f32 v[8:9], v[8:9], 1.0 op_sel_hi:[1,0]
	s_nop 0
	v_div_scale_f32 v11, s[22:23], v9, v9, v10
	v_rcp_f32_e32 v14, v11
	s_nop 0
	v_fma_f32 v15, -v11, v14, 1.0
	v_fmac_f32_e32 v14, v15, v14
	v_div_scale_f32 v15, vcc, v10, v9, v10
	v_mul_f32_e32 v16, v15, v14
	v_fma_f32 v17, -v11, v16, v15
	v_fmac_f32_e32 v16, v17, v14
	v_fma_f32 v11, -v11, v16, v15
	v_div_fmas_f32 v11, v11, v14, v16
	v_div_fixup_f32 v9, v11, v9, v10
	v_div_scale_f32 v10, s[22:23], v8, v8, v5
	v_rcp_f32_e32 v11, v10
	s_nop 0
	v_fma_f32 v14, -v10, v11, 1.0
	v_fmac_f32_e32 v11, v14, v11
	v_div_scale_f32 v14, vcc, v5, v8, v5
	v_mul_f32_e32 v15, v14, v11
	v_fma_f32 v16, -v10, v15, v14
	v_fmac_f32_e32 v15, v16, v11
	v_fma_f32 v10, -v10, v15, v14
	v_div_fmas_f32 v10, v10, v11, v15
	v_div_fixup_f32 v8, v10, v8, v5
	v_pk_mul_f32 v[6:7], v[8:9], v[6:7]
	s_nop 0
	v_cvt_pk_bf16_f32 v5, v6, v7
	s_waitcnt vmcnt(2)
	v_lshlrev_b32_e32 v6, 16, v86
	v_and_b32_e32 v7, 0xffff0000, v86
	global_store_dwordx2 v[18:19], v[4:5], off offset:1600
	v_mul_f32_e32 v4, 0xbfb8aa3b, v6
	v_mul_f32_e32 v5, 0xbfb8aa3b, v7
	v_exp_f32_e32 v4, v4
	v_exp_f32_e32 v5, v5
	s_nop 0
	v_pk_add_f32 v[4:5], v[4:5], 1.0 op_sel_hi:[1,0]
	s_nop 0
	v_div_scale_f32 v8, s[22:23], v5, v5, v7
	v_rcp_f32_e32 v9, v8
	s_nop 0
	v_fma_f32 v10, -v8, v9, 1.0
	v_fmac_f32_e32 v9, v10, v9
	v_div_scale_f32 v10, vcc, v7, v5, v7
	v_mul_f32_e32 v11, v10, v9
	v_fma_f32 v14, -v8, v11, v10
	v_fmac_f32_e32 v11, v14, v9
	v_fma_f32 v8, -v8, v11, v10
	v_div_fmas_f32 v8, v8, v9, v11
	v_div_fixup_f32 v5, v8, v5, v7
	v_div_scale_f32 v7, s[22:23], v4, v4, v6
	v_rcp_f32_e32 v8, v7
	s_nop 0
	v_fma_f32 v9, -v7, v8, 1.0
	v_fmac_f32_e32 v8, v9, v8
	v_div_scale_f32 v9, vcc, v6, v4, v6
	v_mul_f32_e32 v10, v9, v8
	v_fma_f32 v11, -v7, v10, v9
	v_fmac_f32_e32 v10, v11, v8
	v_fma_f32 v7, -v7, v10, v9
	v_div_fmas_f32 v7, v7, v8, v10
	v_div_fixup_f32 v4, v7, v4, v6
	v_pk_mul_f32 v[0:1], v[4:5], v[0:1]
	v_and_b32_e32 v6, 0xffff0000, v87
	v_cvt_pk_bf16_f32 v0, v0, v1
	v_lshlrev_b32_e32 v1, 16, v87
	v_mul_f32_e32 v4, 0xbfb8aa3b, v1
	v_mul_f32_e32 v5, 0xbfb8aa3b, v6
	v_exp_f32_e32 v4, v4
	v_exp_f32_e32 v5, v5
	s_nop 0
	v_pk_add_f32 v[4:5], v[4:5], 1.0 op_sel_hi:[1,0]
	s_nop 0
	v_div_scale_f32 v7, s[22:23], v5, v5, v6
	v_rcp_f32_e32 v8, v7
	s_nop 0
	v_fma_f32 v9, -v7, v8, 1.0
	v_fmac_f32_e32 v8, v9, v8
	v_div_scale_f32 v9, vcc, v6, v5, v6
	v_mul_f32_e32 v10, v9, v8
	v_fma_f32 v11, -v7, v10, v9
	v_fmac_f32_e32 v10, v11, v8
	v_fma_f32 v7, -v7, v10, v9
	v_div_fmas_f32 v7, v7, v8, v10
	v_div_fixup_f32 v5, v7, v5, v6
	v_div_scale_f32 v6, s[22:23], v4, v4, v1
	v_rcp_f32_e32 v7, v6
	s_mov_b64 s[22:23], 0
	v_fma_f32 v8, -v6, v7, 1.0
	v_fmac_f32_e32 v7, v8, v7
	v_div_scale_f32 v8, vcc, v1, v4, v1
	v_mul_f32_e32 v9, v8, v7
	v_fma_f32 v10, -v6, v9, v8
	v_fmac_f32_e32 v9, v10, v7
	v_fma_f32 v6, -v6, v9, v8
	v_div_fmas_f32 v6, v6, v7, v9
	v_div_fixup_f32 v4, v6, v4, v1
	v_pk_mul_f32 v[2:3], v[4:5], v[2:3]
	s_and_b64 vcc, exec, s[40:41]
	v_cvt_pk_bf16_f32 v1, v2, v3
	global_store_dwordx2 v[18:19], v[0:1], off offset:1632
	s_cbranch_vccz .Lma_cont_dil
	s_barrier
	s_branch .LBB0_447
.Lma_cont_dil:
.LBB0_445:
	s_xor_b64 s[40:41], s[22:23], -1
	s_and_b64 vcc, exec, s[40:41]
	s_cbranch_vccnz .LBB0_444
	global_load_dwordx4 v[34:37], v[74:75], off
	global_load_dwordx4 v[38:41], v[74:75], off offset:512
	global_load_dwordx4 v[42:45], v[76:77], off
	global_load_dwordx4 v[46:49], v[76:77], off offset:512
	global_load_dwordx4 v[50:53], v[78:79], off
	global_load_dwordx4 v[54:57], v[78:79], off offset:512
	global_load_dwordx4 v[58:61], v[80:81], off
	global_load_dwordx4 v[62:65], v[80:81], off offset:512
	s_waitcnt vmcnt(7)
	ds_write_b128 v31, v[34:37]
	s_waitcnt vmcnt(6)
	ds_write_b128 v31, v[38:41] offset:36864
	s_waitcnt vmcnt(5)
	ds_write_b128 v99, v[42:45]
	s_waitcnt vmcnt(4)
	ds_write_b128 v99, v[46:49] offset:36864
	s_waitcnt vmcnt(3)
	ds_write_b128 v100, v[50:53]
	s_waitcnt vmcnt(2)
	ds_write_b128 v100, v[54:57] offset:36864
	s_waitcnt vmcnt(1)
	ds_write_b128 v101, v[58:61]
	s_waitcnt vmcnt(0)
	ds_write_b128 v101, v[62:65] offset:36864
	s_branch .LBB0_444

; DI f32x4 mfma16(bf16x8 a, bf16x8 b, f32x4 c) { return __builtin_amdgcn_mfma_f32_16x16x32_bf16(a, b, c, 0, 0, 0); }
; DI void mem_attn_item(ldsp lds, const bf16_t* proj, int ldp, int qmcol, int gatecol, const bf16_t* kv, bf16_t* branch, int b0, int item, int tid, int wid, int lane, const bool stage = true) {
;     ...
;     const int li = lane & 15, quad = lane >> 4;
;     const int tq = 128 * qt + 16 * wid + li;
;     const size_t prow = (size_t)bl * 2048 + tq;
;     bf16x8 qf[2];
; #pragma unroll
;     for (int ks = 0; ks < 2; ++ks) qf[ks] = *(const bf16x8*)(proj + prow * ldp + qmcol + hm * 64 + ks * 32 + quad * 8);
;     u32x2 gtv[4];
; #pragma unroll
;     for (int dt = 0; dt < 4; ++dt) gtv[dt] = *(const u32x2*)(proj + prow * ldp + gatecol + 768 + hm * 64 + quad * 4 + dt * 16);
;     __syncthreads();
;     f32x4 sacc[16];
; #pragma unroll
;     for (int t = 0; t < 16; ++t) {
;         sacc[t] = (f32x4){0.f, 0.f, 0.f, 0.f};
;         const ldsp ka = Kb + (16 * t + li) * KS + quad * 16;
; #pragma unroll
;         for (int ks = 0; ks < 2; ++ks) sacc[t] = mfma16(lds_rd8(ka + ks * 64), qf[ks], sacc[t]);
;     }
.LBB0_511:
	s_add_i32 s15, s93, s14
	s_and_b32 s15, s15, 0x780
	v_add_u32_e32 v94, s15, v13
	v_readlane_b32 s22, v252, 10
	v_ashrrev_i32_e32 v95, 31, v94
	v_readlane_b32 s23, v252, 11
	v_mov_b32_e32 v83, v12
	v_mov_b32_e32 v85, v12
	v_lshl_add_u64 v[0:1], s[22:23], 0, v[94:95]
	v_readlane_b32 s22, v251, 15
	v_readlane_b32 s23, v251, 16
	s_movk_i32 s15, 0x1000
	s_addk_i32 s14, 0x80
	v_mov_b64_e32 v[2:3], s[22:23]
	v_mad_u64_u32 v[2:3], s[22:23], v0, s94, v[2:3]
	v_mad_i32_i24 v3, v1, s94, v3
	v_lshl_add_u64 v[4:5], v[2:3], 0, s[0:1]
	v_lshl_add_u64 v[0:1], v[4:5], 0, v[82:83]
	global_load_dwordx4 v[70:73], v[0:1], off offset:3104
	s_nop 0
	global_load_dwordx4 v[0:3], v[0:1], off offset:3168
	v_lshl_add_u64 v[4:5], v[4:5], 0, v[84:85]
	v_lshl_add_u64 v[6:7], v[4:5], 0, s[26:27]
	v_add_co_u32_e32 v4, vcc, s15, v4
	s_mov_b32 s15, 0xff800000
	s_nop 0
	v_addc_co_u32_e32 v5, vcc, 0, v5, vcc
	global_load_dwordx2 v[92:93], v[4:5], off offset:1056
	global_load_dwordx2 v[90:91], v[6:7], off offset:32
	global_load_dwordx2 v[88:89], v[6:7], off offset:64
	global_load_dwordx2 v[86:87], v[6:7], off offset:96
	s_waitcnt lgkmcnt(0)
	s_cmpk_lg_i32 s14, 0x80
	s_cbranch_scc1 .Lma_nobar_gla
	s_barrier
.Lma_nobar_gla:
	ds_read_b128 v[4:7], v103
	ds_read_b128 v[8:11], v103 offset:64
	s_cmpk_eq_i32 s14, 0x400
	s_waitcnt vmcnt(5) lgkmcnt(1)
	v_mfma_f32_16x16x32_bf16 v[4:7], v[4:7], v[70:73], 0
	ds_read_b128 v[108:111], v103 offset:32320
	s_waitcnt vmcnt(4) lgkmcnt(1)
	v_mfma_f32_16x16x32_bf16 v[66:69], v[8:11], v[0:3], v[4:7]
	ds_read_b128 v[8:11], v103 offset:2368
	s_nop 3
	ds_read_b128 v[4:7], v103 offset:2304
	s_waitcnt lgkmcnt(0)
	v_mfma_f32_16x16x32_bf16 v[4:7], v[4:7], v[70:73], 0
	v_mfma_f32_16x16x32_bf16 v[62:65], v[8:11], v[0:3], v[4:7]
	ds_read_b128 v[8:11], v103 offset:4672
	s_nop 5
	ds_read_b128 v[4:7], v103 offset:4608
	s_waitcnt lgkmcnt(0)
	v_mfma_f32_16x16x32_bf16 v[4:7], v[4:7], v[70:73], 0
	v_mfma_f32_16x16x32_bf16 v[58:61], v[8:11], v[0:3], v[4:7]
	ds_read_b128 v[8:11], v104 offset:64
	s_nop 5
	ds_read_b128 v[4:7], v104
	s_waitcnt lgkmcnt(0)
	v_mfma_f32_16x16x32_bf16 v[4:7], v[4:7], v[70:73], 0
	v_mfma_f32_16x16x32_bf16 v[54:57], v[8:11], v[0:3], v[4:7]
	ds_read_b128 v[8:11], v103 offset:9280
	s_nop 5
	ds_read_b128 v[4:7], v103 offset:9216
	s_waitcnt lgkmcnt(0)
	v_mfma_f32_16x16x32_bf16 v[4:7], v[4:7], v[70:73], 0
	v_mfma_f32_16x16x32_bf16 v[50:53], v[8:11], v[0:3], v[4:7]
	ds_read_b128 v[8:11], v103 offset:11584
	s_nop 5
	ds_read_b128 v[4:7], v103 offset:11520
	s_waitcnt lgkmcnt(0)
	v_mfma_f32_16x16x32_bf16 v[4:7], v[4:7], v[70:73], 0
	v_mfma_f32_16x16x32_bf16 v[46:49], v[8:11], v[0:3], v[4:7]
	ds_read_b128 v[8:11], v103 offset:13888
	s_nop 5
	ds_read_b128 v[4:7], v103 offset:13824
	s_waitcnt lgkmcnt(0)
	v_mfma_f32_16x16x32_bf16 v[4:7], v[4:7], v[70:73], 0
	v_mfma_f32_16x16x32_bf16 v[42:45], v[8:11], v[0:3], v[4:7]
	ds_read_b128 v[8:11], v105 offset:64
	s_nop 5
	ds_read_b128 v[4:7], v105
	s_waitcnt lgkmcnt(0)
	v_mfma_f32_16x16x32_bf16 v[4:7], v[4:7], v[70:73], 0
	v_mfma_f32_16x16x32_bf16 v[38:41], v[8:11], v[0:3], v[4:7]
	ds_read_b128 v[8:11], v103 offset:18496
	s_nop 5
	ds_read_b128 v[4:7], v103 offset:18432
	s_waitcnt lgkmcnt(0)
	v_mfma_f32_16x16x32_bf16 v[4:7], v[4:7], v[70:73], 0
	v_mfma_f32_16x16x32_bf16 v[34:37], v[8:11], v[0:3], v[4:7]
	ds_read_b128 v[8:11], v103 offset:20800
	s_nop 5
	ds_read_b128 v[4:7], v103 offset:20736
	s_waitcnt lgkmcnt(0)
	v_mfma_f32_16x16x32_bf16 v[4:7], v[4:7], v[70:73], 0
	v_mfma_f32_16x16x32_bf16 v[26:29], v[8:11], v[0:3], v[4:7]
	ds_read_b128 v[8:11], v103 offset:23104
	s_nop 5
	ds_read_b128 v[4:7], v103 offset:23040
	s_waitcnt lgkmcnt(0)
	v_mfma_f32_16x16x32_bf16 v[4:7], v[4:7], v[70:73], 0
	v_mfma_f32_16x16x32_bf16 v[22:25], v[8:11], v[0:3], v[4:7]
	ds_read_b128 v[8:11], v106 offset:64
	s_nop 5
	ds_read_b128 v[4:7], v106
	s_waitcnt lgkmcnt(0)
	v_mfma_f32_16x16x32_bf16 v[4:7], v[4:7], v[70:73], 0
	v_mfma_f32_16x16x32_bf16 v[18:21], v[8:11], v[0:3], v[4:7]
	ds_read_b128 v[8:11], v103 offset:27712
	s_nop 5
	ds_read_b128 v[4:7], v103 offset:27648
	s_waitcnt lgkmcnt(0)
	v_mfma_f32_16x16x32_bf16 v[4:7], v[4:7], v[70:73], 0
	v_mfma_f32_16x16x32_bf16 v[14:17], v[8:11], v[0:3], v[4:7]
	ds_read_b128 v[8:11], v103 offset:30016
	s_nop 5
	ds_read_b128 v[4:7], v103 offset:29952
	s_waitcnt lgkmcnt(0)
	v_mfma_f32_16x16x32_bf16 v[4:7], v[4:7], v[70:73], 0
	v_mfma_f32_16x16x32_bf16 v[8:11], v[8:11], v[0:3], v[4:7]
	s_nop 6
	ds_read_b128 v[4:7], v103 offset:32256
	s_waitcnt lgkmcnt(0)
	v_mfma_f32_16x16x32_bf16 v[4:7], v[4:7], v[70:73], 0
	v_mfma_f32_16x16x32_bf16 v[4:7], v[108:111], v[0:3], v[4:7]
	ds_read_b128 v[108:111], v107
	s_waitcnt lgkmcnt(0)
	v_mfma_f32_16x16x32_bf16 v[70:73], v[108:111], v[70:73], 0
	ds_read_b128 v[108:111], v107 offset:64
	s_waitcnt lgkmcnt(0)
; DI f32x4 mfma16(bf16x8 a, bf16x8 b, f32x4 c) { return __builtin_amdgcn_mfma_f32_16x16x32_bf16(a, b, c, 0, 0, 0); }
; DI void mem_attn_item(ldsp lds, const bf16_t* proj, int ldp, int qmcol, int gatecol, const bf16_t* kv, bf16_t* branch, int b0, int item, int tid, int wid, int lane, const bool stage = true) {
;     ...
;     for (int t = 0; t < 16; ++t) {
;         sacc[t] = (f32x4){0.f, 0.f, 0.f, 0.f};
;         const ldsp ka = Kb + (16 * t + li) * KS + quad * 16;
; #pragma unroll
;         for (int ks = 0; ks < 2; ++ks) sacc[t] = mfma16(lds_rd8(ka + ks * 64), qf[ks], sacc[t]);
;     }
;     float mx = -INFINITY;
; #pragma unroll
;     for (int t = 0; t < 16; ++t)
; #pragma unroll
;         for (int j = 0; j < 4; ++j) { const float v = sacc[t][j] * 0.125f; sacc[t][j] = v; mx = fmaxf(mx, v); }
;     mx = fmaxf(mx, __shfl_xor(mx, 16)); mx = fmaxf(mx, __shfl_xor(mx, 32));
	v_mfma_f32_16x16x32_bf16 v[0:3], v[108:111], v[0:3], v[70:73]
	s_nop 4
	v_mul_f32_e32 v70, 0x3e000000, v66
	v_mul_f32_e32 v71, 0x3e000000, v67
	v_max3_f32 v70, v70, s15, v71
	v_mul_f32_e32 v71, 0x3e000000, v68
	v_mul_f32_e32 v72, 0x3e000000, v69
	v_max3_f32 v70, v70, v71, v72
	v_mul_f32_e32 v71, 0x3e000000, v62
	v_mul_f32_e32 v72, 0x3e000000, v63
	v_max3_f32 v70, v70, v71, v72
	v_mul_f32_e32 v71, 0x3e000000, v64
	v_mul_f32_e32 v72, 0x3e000000, v65
	v_max3_f32 v70, v70, v71, v72
	v_mul_f32_e32 v71, 0x3e000000, v58
	v_mul_f32_e32 v72, 0x3e000000, v59
	v_max3_f32 v70, v70, v71, v72
	v_mul_f32_e32 v71, 0x3e000000, v60
	v_mul_f32_e32 v72, 0x3e000000, v61
	v_max3_f32 v70, v70, v71, v72
	v_mul_f32_e32 v71, 0x3e000000, v54
	v_mul_f32_e32 v72, 0x3e000000, v55
	v_max3_f32 v70, v70, v71, v72
	v_mul_f32_e32 v71, 0x3e000000, v56
	v_mul_f32_e32 v72, 0x3e000000, v57
	v_max3_f32 v70, v70, v71, v72
	v_mul_f32_e32 v71, 0x3e000000, v50
	v_mul_f32_e32 v72, 0x3e000000, v51
	v_max3_f32 v70, v70, v71, v72
	v_mul_f32_e32 v71, 0x3e000000, v52
	v_mul_f32_e32 v72, 0x3e000000, v53
	v_max3_f32 v70, v70, v71, v72
	v_mul_f32_e32 v71, 0x3e000000, v46
	v_mul_f32_e32 v72, 0x3e000000, v47
	v_max3_f32 v70, v70, v71, v72
	v_mul_f32_e32 v71, 0x3e000000, v48
	v_mul_f32_e32 v72, 0x3e000000, v49
	v_max3_f32 v70, v70, v71, v72
	v_mul_f32_e32 v71, 0x3e000000, v42
	v_mul_f32_e32 v72, 0x3e000000, v43
	v_max3_f32 v70, v70, v71, v72
	v_mul_f32_e32 v71, 0x3e000000, v44
	v_mul_f32_e32 v72, 0x3e000000, v45
	v_max3_f32 v70, v70, v71, v72
	v_mul_f32_e32 v71, 0x3e000000, v38
	v_mul_f32_e32 v72, 0x3e000000, v39
	v_max3_f32 v70, v70, v71, v72
	v_mul_f32_e32 v71, 0x3e000000, v40
	v_mul_f32_e32 v72, 0x3e000000, v41
	v_max3_f32 v70, v70, v71, v72
	v_mul_f32_e32 v71, 0x3e000000, v34
	v_mul_f32_e32 v72, 0x3e000000, v35
	v_max3_f32 v70, v70, v71, v72
	v_mul_f32_e32 v71, 0x3e000000, v36
	v_mul_f32_e32 v72, 0x3e000000, v37
	v_max3_f32 v70, v70, v71, v72
	v_mul_f32_e32 v71, 0x3e000000, v26
	v_mul_f32_e32 v72, 0x3e000000, v27
	v_max3_f32 v70, v70, v71, v72
	v_mul_f32_e32 v71, 0x3e000000, v28
	v_mul_f32_e32 v72, 0x3e000000, v29
	v_max3_f32 v70, v70, v71, v72
	v_mul_f32_e32 v71, 0x3e000000, v22
	v_mul_f32_e32 v72, 0x3e000000, v23
	v_max3_f32 v70, v70, v71, v72
	v_mul_f32_e32 v71, 0x3e000000, v24
	v_mul_f32_e32 v72, 0x3e000000, v25
	v_max3_f32 v70, v70, v71, v72
	v_mul_f32_e32 v71, 0x3e000000, v18
	v_mul_f32_e32 v72, 0x3e000000, v19
	v_max3_f32 v70, v70, v71, v72
	v_mul_f32_e32 v71, 0x3e000000, v20
	v_mul_f32_e32 v72, 0x3e000000, v21
	v_max3_f32 v70, v70, v71, v72
	v_mul_f32_e32 v71, 0x3e000000, v14
	v_mul_f32_e32 v72, 0x3e000000, v15
	v_max3_f32 v70, v70, v71, v72
	v_mul_f32_e32 v71, 0x3e000000, v16
	v_mul_f32_e32 v72, 0x3e000000, v17
	v_max3_f32 v70, v70, v71, v72
	v_mul_f32_e32 v71, 0x3e000000, v8
	v_mul_f32_e32 v72, 0x3e000000, v9
	v_max3_f32 v70, v70, v71, v72
	v_mul_f32_e32 v71, 0x3e000000, v10
	v_mul_f32_e32 v72, 0x3e000000, v11
	v_max3_f32 v70, v70, v71, v72
	v_mul_f32_e32 v71, 0x3e000000, v4
	v_mul_f32_e32 v72, 0x3e000000, v5
	v_max3_f32 v70, v70, v71, v72
	v_mul_f32_e32 v71, 0x3e000000, v6
	v_mul_f32_e32 v72, 0x3e000000, v7
	v_max3_f32 v70, v70, v71, v72
	v_mul_f32_e32 v71, 0x3e000000, v0
	v_mul_f32_e32 v72, 0x3e000000, v1
	v_max3_f32 v70, v70, v71, v72
	v_mul_f32_e32 v71, 0x3e000000, v2
	v_mul_f32_e32 v72, 0x3e000000, v3
	v_max3_f32 v70, v70, v71, v72
	ds_bpermute_b32 v71, v33, v70
	v_min3_f32 v224, v66, v67, v68
	v_min3_f32 v224, v224, v69, v62
	v_min3_f32 v224, v224, v63, v64
	v_min3_f32 v224, v224, v65, v58
	v_min3_f32 v224, v224, v59, v60
	v_min3_f32 v224, v224, v61, v54
	v_min3_f32 v224, v224, v55, v56
	v_min3_f32 v224, v224, v57, v50
	v_min3_f32 v224, v224, v51, v52
	v_min3_f32 v224, v224, v53, v46
	v_min3_f32 v224, v224, v47, v48
	v_min3_f32 v224, v224, v49, v42
	v_min3_f32 v224, v224, v43, v44
	v_min3_f32 v224, v224, v45, v38
	v_min3_f32 v224, v224, v39, v40
	v_min3_f32 v224, v224, v41, v34
	s_waitcnt lgkmcnt(0)
	v_max_f32_e32 v71, v71, v71
	v_max_f32_e32 v70, v70, v71
	ds_bpermute_b32 v71, v96, v70
	v_min3_f32 v224, v224, v35, v36
	v_min3_f32 v224, v224, v37, v26
	v_min3_f32 v224, v224, v27, v28
	v_min3_f32 v224, v224, v29, v22
	v_min3_f32 v224, v224, v23, v24
	v_min3_f32 v224, v224, v25, v18
	v_min3_f32 v224, v224, v19, v20
	v_min3_f32 v224, v224, v21, v14
	v_min3_f32 v224, v224, v15, v16
	v_min3_f32 v224, v224, v17, v8
	v_min3_f32 v224, v224, v9, v10
	v_min3_f32 v224, v224, v11, v4
	v_min3_f32 v224, v224, v5, v6
	v_min3_f32 v224, v224, v7, v0
	v_min3_f32 v224, v224, v1, v2
	v_min_f32_e32 v224, v224, v3
	s_waitcnt lgkmcnt(0)
	v_max_f32_e32 v71, v71, v71
	v_max_f32_e32 v72, v70, v71
	v_fma_f32 v225, v224, s85, -v72
	v_mul_f32_e32 v225, 0x3fb8aa3b, v225
	v_cmp_gt_f32_e32 vcc, s86, v225
	s_cbranch_vccnz .Lma_slow_gla
; DI void mem_attn_item(ldsp lds, const bf16_t* proj, int ldp, int qmcol, int gatecol, const bf16_t* kv, bf16_t* branch, int b0, int item, int tid, int wid, int lane, const bool stage = true) {
;     ...
;     float den = 0.f;
; #pragma unroll
;     for (int t = 0; t < 16; ++t)
; #pragma unroll
;         for (int j = 0; j < 4; ++j) { const float pv = exp2f((sacc[t][j] - mx) * 1.4426950408889634f); sacc[t][j] = pv; den += pv; }
;     den += __shfl_xor(den, 16); den += __shfl_xor(den, 32);
	v_fma_f32 v66, v66, s85, -v72
	v_mul_f32_e32 v70, 0x3fb8aa3b, v66
	v_fma_f32 v67, v67, s85, -v72
	v_fma_f32 v68, v68, s85, -v72
	v_exp_f32_e32 v66, v70
	v_mul_f32_e32 v71, 0x3fb8aa3b, v68
	v_fma_f32 v69, v69, s85, -v72
	v_mul_f32_e32 v70, 0x3fb8aa3b, v67
	v_fma_f32 v62, v62, s85, -v72
	v_fma_f32 v63, v63, s85, -v72
	v_exp_f32_e32 v67, v70
	v_fma_f32 v58, v58, s85, -v72
	v_exp_f32_e32 v68, v71
	v_add_f32_e32 v70, v66, v67
	v_fma_f32 v59, v59, s85, -v72
	v_mul_f32_e32 v71, 0x3fb8aa3b, v69
	v_add_f32_e32 v70, v68, v70
	v_fma_f32 v60, v60, s85, -v72
	v_exp_f32_e32 v69, v71
	v_fma_f32 v61, v61, s85, -v72
	v_fma_f32 v54, v54, s85, -v72
	v_add_f32_e32 v71, v69, v70
	v_mul_f32_e32 v70, 0x3fb8aa3b, v62
	v_fma_f32 v55, v55, s85, -v72
	v_fma_f32 v56, v56, s85, -v72
	v_exp_f32_e32 v62, v70
	v_fma_f32 v57, v57, s85, -v72
	v_fma_f32 v50, v50, s85, -v72
	v_mov_b32_e32 v70, v62
	v_add_f32_e32 v62, v70, v71
	v_mul_f32_e32 v71, 0x3fb8aa3b, v63
	v_fma_f32 v51, v51, s85, -v72
	v_fma_f32 v52, v52, s85, -v72
	v_exp_f32_e32 v63, v71
	v_fma_f32 v53, v53, s85, -v72
	v_fma_f32 v46, v46, s85, -v72
	v_mov_b32_e32 v71, v63
	v_fma_f32 v63, v64, s85, -v72
	v_mul_f32_e32 v64, 0x3fb8aa3b, v63
	v_fma_f32 v47, v47, s85, -v72
	v_fma_f32 v48, v48, s85, -v72
	v_exp_f32_e32 v63, v64
	v_fma_f32 v49, v49, s85, -v72
	v_fma_f32 v42, v42, s85, -v72
	v_mov_b32_e32 v64, v63
	v_fma_f32 v63, v65, s85, -v72
	v_mul_f32_e32 v65, 0x3fb8aa3b, v63
	v_fma_f32 v43, v43, s85, -v72
	v_fma_f32 v44, v44, s85, -v72
	v_exp_f32_e32 v63, v65
	v_fma_f32 v45, v45, s85, -v72
	v_fma_f32 v38, v38, s85, -v72
	v_mov_b32_e32 v65, v63
	v_mul_f32_e32 v63, 0x3fb8aa3b, v58
	v_fma_f32 v39, v39, s85, -v72
	v_fma_f32 v40, v40, s85, -v72
	v_exp_f32_e32 v58, v63
	v_fma_f32 v41, v41, s85, -v72
	v_fma_f32 v34, v34, s85, -v72
	v_mul_f32_e32 v63, 0x3fb8aa3b, v59
	v_fma_f32 v35, v35, s85, -v72
	v_fma_f32 v36, v36, s85, -v72
	v_exp_f32_e32 v59, v63
	v_add_f32_e32 v62, v71, v62
	v_add_f32_e32 v62, v64, v62
	v_mul_f32_e32 v63, 0x3fb8aa3b, v60
	v_add_f32_e32 v62, v65, v62
	v_add_f32_e32 v62, v58, v62
	v_exp_f32_e32 v60, v63
	v_add_f32_e32 v62, v59, v62
	v_fma_f32 v37, v37, s85, -v72
	v_mul_f32_e32 v63, 0x3fb8aa3b, v61
	v_add_f32_e32 v62, v60, v62
	v_fma_f32 v26, v26, s85, -v72
	v_exp_f32_e32 v61, v63
	v_fma_f32 v27, v27, s85, -v72
	v_fma_f32 v28, v28, s85, -v72
	v_mul_f32_e32 v63, 0x3fb8aa3b, v54
	v_add_f32_e32 v62, v61, v62
	v_fma_f32 v29, v29, s85, -v72
	v_exp_f32_e32 v54, v63
	v_fma_f32 v22, v22, s85, -v72
	v_fma_f32 v23, v23, s85, -v72
	v_mul_f32_e32 v63, 0x3fb8aa3b, v55
	v_add_f32_e32 v62, v54, v62
	v_fma_f32 v24, v24, s85, -v72
	v_exp_f32_e32 v55, v63
	v_fma_f32 v25, v25, s85, -v72
	v_fma_f32 v18, v18, s85, -v72
	v_mul_f32_e32 v63, 0x3fb8aa3b, v56
	v_add_f32_e32 v62, v55, v62
	v_fma_f32 v19, v19, s85, -v72
	v_exp_f32_e32 v56, v63
	v_fma_f32 v14, v14, s85, -v72
	v_fma_f32 v15, v15, s85, -v72
	v_mul_f32_e32 v63, 0x3fb8aa3b, v57
	v_add_f32_e32 v62, v56, v62
	v_fma_f32 v16, v16, s85, -v72
	v_exp_f32_e32 v57, v63
	v_fma_f32 v17, v17, s85, -v72
	v_fma_f32 v8, v8, s85, -v72
	v_mul_f32_e32 v63, 0x3fb8aa3b, v50
	v_add_f32_e32 v62, v57, v62
	v_fma_f32 v9, v9, s85, -v72
	v_exp_f32_e32 v50, v63
	v_fma_f32 v10, v10, s85, -v72
	v_fma_f32 v11, v11, s85, -v72
	v_mul_f32_e32 v63, 0x3fb8aa3b, v51
	v_add_f32_e32 v62, v50, v62
	v_fma_f32 v4, v4, s85, -v72
	v_exp_f32_e32 v51, v63
	v_fma_f32 v5, v5, s85, -v72
	v_fma_f32 v6, v6, s85, -v72
	v_mul_f32_e32 v63, 0x3fb8aa3b, v52
	v_add_f32_e32 v62, v51, v62
	v_fma_f32 v7, v7, s85, -v72
	v_exp_f32_e32 v52, v63
	v_fma_f32 v0, v0, s85, -v72
	v_fma_f32 v1, v1, s85, -v72
	v_mul_f32_e32 v63, 0x3fb8aa3b, v53
	v_add_f32_e32 v62, v52, v62
	v_fma_f32 v2, v2, s85, -v72
	v_exp_f32_e32 v53, v63
	v_fma_f32 v3, v3, s85, -v72
	v_cvt_pk_bf16_f32 v66, v66, v67
	v_mul_f32_e32 v63, 0x3fb8aa3b, v46
	v_add_f32_e32 v62, v53, v62
	v_cvt_pk_bf16_f32 v67, v68, v69
	v_exp_f32_e32 v46, v63
	v_cvt_pk_bf16_f32 v68, v70, v71
	v_cvt_pk_bf16_f32 v69, v64, v65
	v_mul_f32_e32 v63, 0x3fb8aa3b, v47
	v_add_f32_e32 v62, v46, v62
	v_cvt_pk_bf16_f32 v58, v58, v59
	v_exp_f32_e32 v47, v63
	v_cvt_pk_bf16_f32 v59, v60, v61
	v_cvt_pk_bf16_f32 v60, v54, v55
	v_mul_f32_e32 v63, 0x3fb8aa3b, v48
	v_add_f32_e32 v62, v47, v62
	v_cvt_pk_bf16_f32 v61, v56, v57
	v_exp_f32_e32 v48, v63
	v_cvt_pk_bf16_f32 v50, v50, v51
	v_cvt_pk_bf16_f32 v51, v52, v53
	v_mul_f32_e32 v63, 0x3fb8aa3b, v49
	v_add_f32_e32 v62, v48, v62
	v_cvt_pk_bf16_f32 v52, v46, v47
	v_exp_f32_e32 v49, v63
	v_mul_f32_e32 v63, 0x3fb8aa3b, v42
	v_add_f32_e32 v62, v49, v62
	v_cvt_pk_bf16_f32 v53, v48, v49
	v_exp_f32_e32 v42, v63
	v_mul_f32_e32 v63, 0x3fb8aa3b, v43
	v_add_f32_e32 v62, v42, v62
	s_nop 0
	v_exp_f32_e32 v43, v63
	v_mul_f32_e32 v63, 0x3fb8aa3b, v44
	v_add_f32_e32 v62, v43, v62
	v_cvt_pk_bf16_f32 v42, v42, v43
	v_exp_f32_e32 v44, v63
	v_mul_f32_e32 v63, 0x3fb8aa3b, v45
	v_add_f32_e32 v62, v44, v62
	s_nop 0
	v_exp_f32_e32 v45, v63
	v_mul_f32_e32 v63, 0x3fb8aa3b, v38
	v_add_f32_e32 v62, v45, v62
	v_cvt_pk_bf16_f32 v43, v44, v45
	v_exp_f32_e32 v38, v63
	v_mul_f32_e32 v63, 0x3fb8aa3b, v39
	v_add_f32_e32 v62, v38, v62
	s_nop 0
	v_exp_f32_e32 v39, v63
	v_mul_f32_e32 v63, 0x3fb8aa3b, v40
	v_add_f32_e32 v62, v39, v62
	v_cvt_pk_bf16_f32 v44, v38, v39
	v_exp_f32_e32 v40, v63
	v_mul_f32_e32 v63, 0x3fb8aa3b, v41
	v_add_f32_e32 v62, v40, v62
	s_nop 0
	v_exp_f32_e32 v41, v63
	v_mul_f32_e32 v63, 0x3fb8aa3b, v34
	v_add_f32_e32 v62, v41, v62
	v_cvt_pk_bf16_f32 v45, v40, v41
	v_exp_f32_e32 v34, v63
	v_mul_f32_e32 v63, 0x3fb8aa3b, v35
	v_add_f32_e32 v62, v34, v62
	s_nop 0
	v_exp_f32_e32 v35, v63
	v_mul_f32_e32 v63, 0x3fb8aa3b, v36
	v_add_f32_e32 v62, v35, v62
	v_cvt_pk_bf16_f32 v34, v34, v35
; DI unsigned cvt_pk_bf16(float lo, float hi) { const f32x2_t v = {lo, hi}; const bf16v2_t b = __builtin_convertvector(v, bf16v2_t); return __builtin_bit_cast(unsigned, b); }
; DI f32x4 mfma16(bf16x8 a, bf16x8 b, f32x4 c) { return __builtin_amdgcn_mfma_f32_16x16x32_bf16(a, b, c, 0, 0, 0); }
; DI void mem_attn_item(ldsp lds, const bf16_t* proj, int ldp, int qmcol, int gatecol, const bf16_t* kv, bf16_t* branch, int b0, int item, int tid, int wid, int lane, const bool stage = true) {
;     ...
;     float den = 0.f;
; #pragma unroll
;     for (int t = 0; t < 16; ++t)
; #pragma unroll
;         for (int j = 0; j < 4; ++j) { const float pv = exp2f((sacc[t][j] - mx) * 1.4426950408889634f); sacc[t][j] = pv; den += pv; }
;     den += __shfl_xor(den, 16); den += __shfl_xor(den, 32);
;     f32x4 oacc[4];
; #pragma unroll
;     for (int dt = 0; dt < 4; ++dt) oacc[dt] = (f32x4){0.f, 0.f, 0.f, 0.f};
; #pragma unroll
;     for (int kt = 0; kt < 8; ++kt) {
;         u32x4 pw; pw.x = cvt_pk_bf16(sacc[2 * kt][0], sacc[2 * kt][1]); pw.y = cvt_pk_bf16(sacc[2 * kt][2], sacc[2 * kt][3]);
;         pw.z = cvt_pk_bf16(sacc[2 * kt + 1][0], sacc[2 * kt + 1][1]); pw.w = cvt_pk_bf16(sacc[2 * kt + 1][2], sacc[2 * kt + 1][3]);
;         const bf16x8 pf = __builtin_bit_cast(bf16x8, pw);
;         const ldsp va = Vb + (32 * kt + quad * 4 + (li >> 2)) * KS + (li & 3) * 8;
; #pragma unroll
;         for (int dt = 0; dt < 4; ++dt) oacc[dt] = mfma16(lds_tr8(va + dt * 32, va + 16 * KS + dt * 32), pf, oacc[dt]);
;     }
	v_exp_f32_e32 v36, v63
	v_mul_f32_e32 v63, 0x3fb8aa3b, v37
	v_add_f32_e32 v62, v36, v62
	s_nop 0
	v_exp_f32_e32 v37, v63
	v_mul_f32_e32 v63, 0x3fb8aa3b, v26
	v_add_f32_e32 v62, v37, v62
	v_cvt_pk_bf16_f32 v35, v36, v37
	v_exp_f32_e32 v26, v63
	v_mul_f32_e32 v63, 0x3fb8aa3b, v27
	v_add_f32_e32 v62, v26, v62
	s_nop 0
	v_exp_f32_e32 v27, v63
	s_nop 0
	v_add_f32_e32 v63, v27, v62
	v_mul_f32_e32 v62, 0x3fb8aa3b, v28
	v_cvt_pk_bf16_f32 v36, v26, v27
	s_nop 0
	v_exp_f32_e32 v28, v62
	s_nop 0
	v_mov_b32_e32 v62, v28
	v_add_f32_e32 v28, v62, v63
	v_mul_f32_e32 v63, 0x3fb8aa3b, v29
	s_nop 1
	v_exp_f32_e32 v29, v63
	s_nop 0
	v_mov_b32_e32 v63, v29
	v_mul_f32_e32 v29, 0x3fb8aa3b, v22
	v_add_f32_e32 v28, v63, v28
	v_cvt_pk_bf16_f32 v37, v62, v63
	v_exp_f32_e32 v22, v29
	v_mul_f32_e32 v29, 0x3fb8aa3b, v23
	v_add_f32_e32 v28, v22, v28
	s_nop 0
	v_exp_f32_e32 v23, v29
	v_mul_f32_e32 v29, 0x3fb8aa3b, v24
	v_add_f32_e32 v28, v23, v28
	v_cvt_pk_bf16_f32 v22, v22, v23
	v_exp_f32_e32 v24, v29
	v_mul_f32_e32 v29, 0x3fb8aa3b, v25
	v_add_f32_e32 v28, v24, v28
	s_nop 0
	v_exp_f32_e32 v25, v29
	s_nop 0
	v_add_f32_e32 v29, v25, v28
	v_mul_f32_e32 v28, 0x3fb8aa3b, v18
	v_cvt_pk_bf16_f32 v23, v24, v25
	s_nop 0
	v_exp_f32_e32 v18, v28
	s_nop 0
	v_mov_b32_e32 v28, v18
	v_add_f32_e32 v18, v28, v29
	v_mul_f32_e32 v29, 0x3fb8aa3b, v19
	s_nop 1
	v_exp_f32_e32 v19, v29
	s_nop 0
	v_mov_b32_e32 v29, v19
	v_fma_f32 v19, v20, s85, -v72
	v_mul_f32_e32 v20, 0x3fb8aa3b, v19
	v_add_f32_e32 v18, v29, v18
	v_cvt_pk_bf16_f32 v24, v28, v29
	v_exp_f32_e32 v19, v20
	s_nop 0
	v_mov_b32_e32 v20, v19
	v_fma_f32 v19, v21, s85, -v72
	v_mul_f32_e32 v21, 0x3fb8aa3b, v19
	ds_read_b64_tr_b16 v[72:73], v97 offset:39168
	ds_read_b64_tr_b16 v[70:71], v97 offset:36864
	ds_read_b64_tr_b16 v[108:109], v97 offset:36896
	v_exp_f32_e32 v19, v21
	ds_read_b64_tr_b16 v[110:111], v97 offset:39200
	ds_read_b64_tr_b16 v[112:113], v97 offset:36928
	ds_read_b64_tr_b16 v[114:115], v97 offset:39232
	v_mov_b32_e32 v21, v19
	v_mul_f32_e32 v19, 0x3fb8aa3b, v14
	ds_read_b64_tr_b16 v[116:117], v97 offset:36960
	ds_read_b64_tr_b16 v[118:119], v97 offset:39264
	v_exp_f32_e32 v14, v19
	ds_read_b64_tr_b16 v[54:55], v97 offset:41472
	ds_read_b64_tr_b16 v[56:57], v97 offset:43776
	s_waitcnt lgkmcnt(8)
	v_mfma_f32_16x16x32_bf16 v[70:73], v[70:73], v[66:69], 0
	v_mul_f32_e32 v19, 0x3fb8aa3b, v15
	s_waitcnt lgkmcnt(6)
	v_mfma_f32_16x16x32_bf16 v[108:111], v[108:111], v[66:69], 0
	v_cvt_pk_bf16_f32 v25, v20, v21
	v_exp_f32_e32 v15, v19
	s_waitcnt lgkmcnt(4)
	v_mfma_f32_16x16x32_bf16 v[112:115], v[112:115], v[66:69], 0
	v_add_f32_e32 v18, v20, v18
	v_mul_f32_e32 v19, 0x3fb8aa3b, v16
	s_waitcnt lgkmcnt(2)
	v_mfma_f32_16x16x32_bf16 v[64:67], v[116:119], v[66:69], 0
	v_add_f32_e32 v18, v21, v18
	v_exp_f32_e32 v16, v19
	s_waitcnt lgkmcnt(0)
	v_mfma_f32_16x16x32_bf16 v[54:57], v[54:57], v[58:61], v[70:73]
	ds_read_b64_tr_b16 v[68:69], v97 offset:41504
	s_nop 1
	ds_read_b64_tr_b16 v[70:71], v97 offset:43808
	v_mul_f32_e32 v19, 0x3fb8aa3b, v17
	s_waitcnt lgkmcnt(0)
	v_mfma_f32_16x16x32_bf16 v[68:71], v[68:71], v[58:61], v[108:111]
	v_exp_f32_e32 v17, v19
	s_nop 1
	ds_read_b64_tr_b16 v[108:109], v97 offset:41536
	ds_read_b64_tr_b16 v[110:111], v97 offset:43840
	s_waitcnt lgkmcnt(0)
	v_mfma_f32_16x16x32_bf16 v[108:111], v[108:111], v[58:61], v[112:115]
	v_mul_f32_e32 v19, 0x3fb8aa3b, v8
	s_nop 1
	ds_read_b64_tr_b16 v[112:113], v97 offset:41568
	ds_read_b64_tr_b16 v[114:115], v97 offset:43872
	v_exp_f32_e32 v8, v19
	ds_read_b64_tr_b16 v[46:47], v97 offset:46080
	ds_read_b64_tr_b16 v[48:49], v97 offset:48384
	s_waitcnt lgkmcnt(0)
	v_mfma_f32_16x16x32_bf16 v[46:49], v[46:49], v[50:53], v[54:57]
	v_mul_f32_e32 v19, 0x3fb8aa3b, v9
	s_nop 1
	ds_read_b64_tr_b16 v[54:55], v97 offset:46112
	ds_read_b64_tr_b16 v[56:57], v97 offset:48416
	v_exp_f32_e32 v9, v19
	v_mfma_f32_16x16x32_bf16 v[58:61], v[112:115], v[58:61], v[64:67]
	s_nop 2
	ds_read_b64_tr_b16 v[64:65], v97 offset:46144
	ds_read_b64_tr_b16 v[66:67], v97 offset:48448
	v_mul_f32_e32 v19, 0x3fb8aa3b, v10
	s_waitcnt lgkmcnt(2)
; DI unsigned cvt_pk_bf16(float lo, float hi) { const f32x2_t v = {lo, hi}; const bf16v2_t b = __builtin_convertvector(v, bf16v2_t); return __builtin_bit_cast(unsigned, b); }
; DI f32x4 mfma16(bf16x8 a, bf16x8 b, f32x4 c) { return __builtin_amdgcn_mfma_f32_16x16x32_bf16(a, b, c, 0, 0, 0); }
; DI void mem_attn_item(ldsp lds, const bf16_t* proj, int ldp, int qmcol, int gatecol, const bf16_t* kv, bf16_t* branch, int b0, int item, int tid, int wid, int lane, const bool stage = true) {
;     ...
;     for (int t = 0; t < 16; ++t)
; #pragma unroll
;         for (int j = 0; j < 4; ++j) { const float pv = exp2f((sacc[t][j] - mx) * 1.4426950408889634f); sacc[t][j] = pv; den += pv; }
;     den += __shfl_xor(den, 16); den += __shfl_xor(den, 32);
;     f32x4 oacc[4];
; #pragma unroll
;     for (int dt = 0; dt < 4; ++dt) oacc[dt] = (f32x4){0.f, 0.f, 0.f, 0.f};
; #pragma unroll
;     for (int kt = 0; kt < 8; ++kt) {
;         u32x4 pw; pw.x = cvt_pk_bf16(sacc[2 * kt][0], sacc[2 * kt][1]); pw.y = cvt_pk_bf16(sacc[2 * kt][2], sacc[2 * kt][3]);
;         pw.z = cvt_pk_bf16(sacc[2 * kt + 1][0], sacc[2 * kt + 1][1]); pw.w = cvt_pk_bf16(sacc[2 * kt + 1][2], sacc[2 * kt + 1][3]);
;         const bf16x8 pf = __builtin_bit_cast(bf16x8, pw);
;         const ldsp va = Vb + (32 * kt + quad * 4 + (li >> 2)) * KS + (li & 3) * 8;
; #pragma unroll
;         for (int dt = 0; dt < 4; ++dt) oacc[dt] = mfma16(lds_tr8(va + dt * 32, va + 16 * KS + dt * 32), pf, oacc[dt]);
;     }
	v_mfma_f32_16x16x32_bf16 v[54:57], v[54:57], v[50:53], v[68:71]
	s_nop 2
	ds_read_b64_tr_b16 v[68:69], v97 offset:46176
	ds_read_b64_tr_b16 v[70:71], v97 offset:48480
	v_exp_f32_e32 v10, v19
	ds_read_b64_tr_b16 v[38:39], v97 offset:50688
	ds_read_b64_tr_b16 v[40:41], v97 offset:52992
	s_waitcnt lgkmcnt(0)
	v_mfma_f32_16x16x32_bf16 v[38:41], v[38:41], v[42:45], v[46:49]
	v_mul_f32_e32 v19, 0x3fb8aa3b, v11
	s_nop 1
	ds_read_b64_tr_b16 v[46:47], v97 offset:50720
	ds_read_b64_tr_b16 v[48:49], v97 offset:53024
	v_exp_f32_e32 v11, v19
	v_mfma_f32_16x16x32_bf16 v[64:67], v[64:67], v[50:53], v[108:111]
	v_add_f32_e32 v18, v14, v18
	v_mul_f32_e32 v19, 0x3fb8aa3b, v4
	v_mfma_f32_16x16x32_bf16 v[50:53], v[68:71], v[50:53], v[58:61]
	v_add_f32_e32 v18, v15, v18
	v_exp_f32_e32 v4, v19
	s_waitcnt lgkmcnt(0)
	v_mfma_f32_16x16x32_bf16 v[46:49], v[46:49], v[42:45], v[54:57]
	s_nop 2
	ds_read_b64_tr_b16 v[54:55], v97 offset:50752
	ds_read_b64_tr_b16 v[56:57], v97 offset:53056
	v_mul_f32_e32 v19, 0x3fb8aa3b, v5
	ds_read_b64_tr_b16 v[58:59], v97 offset:50784
	ds_read_b64_tr_b16 v[60:61], v97 offset:53088
	v_exp_f32_e32 v5, v19
	s_waitcnt lgkmcnt(2)
	v_mfma_f32_16x16x32_bf16 v[54:57], v[54:57], v[42:45], v[64:67]
	v_add_f32_e32 v18, v16, v18
	v_mul_f32_e32 v19, 0x3fb8aa3b, v6
	s_waitcnt lgkmcnt(0)
	v_mfma_f32_16x16x32_bf16 v[42:45], v[58:61], v[42:45], v[50:53]
	s_nop 2
	ds_read_b64_tr_b16 v[50:51], v97 offset:55296
	ds_read_b64_tr_b16 v[52:53], v97 offset:57600
	v_exp_f32_e32 v6, v19
	s_waitcnt lgkmcnt(0)
	v_mfma_f32_16x16x32_bf16 v[38:41], v[50:53], v[34:37], v[38:41]
	ds_read_b64_tr_b16 v[50:51], v97 offset:55328
	ds_read_b64_tr_b16 v[52:53], v97 offset:57632
	v_mul_f32_e32 v19, 0x3fb8aa3b, v7
	s_waitcnt lgkmcnt(0)
	v_mfma_f32_16x16x32_bf16 v[46:49], v[50:53], v[34:37], v[46:49]
	v_exp_f32_e32 v7, v19
	ds_read_b64_tr_b16 v[50:51], v97 offset:55360
	ds_read_b64_tr_b16 v[52:53], v97 offset:57664
	s_waitcnt lgkmcnt(0)
	v_mfma_f32_16x16x32_bf16 v[50:53], v[50:53], v[34:37], v[54:57]
	v_mul_f32_e32 v19, 0x3fb8aa3b, v0
	s_nop 1
	ds_read_b64_tr_b16 v[54:55], v97 offset:55392
	ds_read_b64_tr_b16 v[56:57], v97 offset:57696
	v_exp_f32_e32 v0, v19
	ds_read_b64_tr_b16 v[26:27], v97 offset:59904
	ds_read_b64_tr_b16 v[28:29], v97 offset:62208
	s_waitcnt lgkmcnt(0)
	v_mfma_f32_16x16x32_bf16 v[26:29], v[26:29], v[22:25], v[38:41]
	v_mul_f32_e32 v19, 0x3fb8aa3b, v1
	s_nop 1
	ds_read_b64_tr_b16 v[38:39], v97 offset:59936
	ds_read_b64_tr_b16 v[40:41], v97 offset:62240
	v_exp_f32_e32 v1, v19
	v_mfma_f32_16x16x32_bf16 v[34:37], v[54:57], v[34:37], v[42:45]
	s_nop 2
	ds_read_b64_tr_b16 v[42:43], v97 offset:59968
	ds_read_b64_tr_b16 v[44:45], v97 offset:62272
	v_add_f32_e32 v18, v17, v18
	s_waitcnt lgkmcnt(2)
	v_mfma_f32_16x16x32_bf16 v[38:41], v[38:41], v[22:25], v[46:49]
	s_nop 2
	ds_read_b64_tr_b16 v[46:47], v97 offset:60000
	ds_read_b64_tr_b16 v[48:49], v97 offset:62304
	v_add_f32_e32 v18, v8, v18
	v_mul_f32_e32 v19, 0x3fb8aa3b, v2
	v_add_f32_e32 v18, v9, v18
	v_add_f32_e32 v18, v10, v18
	v_add_f32_e32 v18, v11, v18
	s_waitcnt lgkmcnt(2)
	v_mfma_f32_16x16x32_bf16 v[42:45], v[42:45], v[22:25], v[50:53]
	v_cvt_pk_bf16_f32 v14, v14, v15
	v_cvt_pk_bf16_f32 v15, v16, v17
	v_cvt_pk_bf16_f32 v16, v8, v9
	s_waitcnt lgkmcnt(0)
	v_mfma_f32_16x16x32_bf16 v[20:23], v[46:49], v[22:25], v[34:37]
	v_cvt_pk_bf16_f32 v17, v10, v11
	ds_read_b64_tr_b16 v[8:9], v97 offset:64512
	ds_read_b64_tr_b16 v[10:11], v98 offset:29952
	ds_read_b64_tr_b16 v[36:37], v98 offset:29984
	ds_read_b64_tr_b16 v[34:35], v97 offset:64544
	v_exp_f32_e32 v2, v19
	v_add_f32_e32 v18, v4, v18
	v_add_f32_e32 v18, v5, v18
	v_mul_f32_e32 v19, 0x3fb8aa3b, v3
	v_add_f32_e32 v18, v6, v18
	s_waitcnt lgkmcnt(2)
	v_mfma_f32_16x16x32_bf16 v[8:11], v[8:11], v[14:17], v[26:29]
	v_exp_f32_e32 v3, v19
	s_waitcnt lgkmcnt(0)
	v_mfma_f32_16x16x32_bf16 v[24:27], v[34:37], v[14:17], v[38:41]
	ds_read_b64_tr_b16 v[34:35], v97 offset:64576
	ds_read_b64_tr_b16 v[36:37], v98 offset:30016
	s_nop 0
	ds_read_b64_tr_b16 v[38:39], v97 offset:64608
	ds_read_b64_tr_b16 v[40:41], v98 offset:30048
	v_add_f32_e32 v18, v7, v18
	v_add_f32_e32 v18, v0, v18
	v_add_f32_e32 v18, v1, v18
	v_add_f32_e32 v18, v2, v18
	s_branch .Lma_join_gla

; DI unsigned cvt_pk_bf16(float lo, float hi) { const f32x2_t v = {lo, hi}; const bf16v2_t b = __builtin_convertvector(v, bf16v2_t); return __builtin_bit_cast(unsigned, b); }
; DI float bf_lo(unsigned u) { return __uint_as_float(u << 16); }
; DI float bf_hi(unsigned u) { return __uint_as_float(u & 0xffff0000u); }
; DI f32x4 mfma16(bf16x8 a, bf16x8 b, f32x4 c) { return __builtin_amdgcn_mfma_f32_16x16x32_bf16(a, b, c, 0, 0, 0); }
; DI float silu_f(float x) { return x / (1.0f + __expf(-x)); }
; DI void mem_attn_item(ldsp lds, const bf16_t* proj, int ldp, int qmcol, int gatecol, const bf16_t* kv, bf16_t* branch, int b0, int item, int tid, int wid, int lane, const bool stage = true) {
;     ...
;     den += __shfl_xor(den, 16); den += __shfl_xor(den, 32);
;     f32x4 oacc[4];
; #pragma unroll
;     for (int dt = 0; dt < 4; ++dt) oacc[dt] = (f32x4){0.f, 0.f, 0.f, 0.f};
; #pragma unroll
;     for (int kt = 0; kt < 8; ++kt) {
;         u32x4 pw; pw.x = cvt_pk_bf16(sacc[2 * kt][0], sacc[2 * kt][1]); pw.y = cvt_pk_bf16(sacc[2 * kt][2], sacc[2 * kt][3]);
;         pw.z = cvt_pk_bf16(sacc[2 * kt + 1][0], sacc[2 * kt + 1][1]); pw.w = cvt_pk_bf16(sacc[2 * kt + 1][2], sacc[2 * kt + 1][3]);
;         const bf16x8 pf = __builtin_bit_cast(bf16x8, pw);
;         const ldsp va = Vb + (32 * kt + quad * 4 + (li >> 2)) * KS + (li & 3) * 8;
; #pragma unroll
;         for (int dt = 0; dt < 4; ++dt) oacc[dt] = mfma16(lds_tr8(va + dt * 32, va + 16 * KS + dt * 32), pf, oacc[dt]);
;     }
;     const float inv = 1.0f / den;
;     bf16_t* dst = branch + ((size_t)(b0 + bl) * 2048 + tq) * 1024 + 768 + hm * 64 + quad * 4;
; #pragma unroll
;     for (int dt = 0; dt < 4; ++dt) {
;         const u32x2 gt = gtv[dt];
;         u32x2 o;
;         o.x = cvt_pk_bf16(oacc[dt][0] * inv * silu_f(bf_lo(gt.x)), oacc[dt][1] * inv * silu_f(bf_hi(gt.x)));
;         o.y = cvt_pk_bf16(oacc[dt][2] * inv * silu_f(bf_lo(gt.y)), oacc[dt][3] * inv * silu_f(bf_hi(gt.y)));
;         *(u32x2*)(dst + dt * 16) = o;
;     }
.Lma_join_gla:
	v_add_f32_e32 v18, v3, v18
	s_waitcnt lgkmcnt(0)
	v_mfma_f32_16x16x32_bf16 v[20:23], v[38:41], v[14:17], v[20:23]
	v_cvt_pk_bf16_f32 v40, v0, v1
	v_cvt_pk_bf16_f32 v41, v2, v3
	ds_read_b64_tr_b16 v[0:1], v98 offset:32256
	ds_read_b64_tr_b16 v[2:3], v98 offset:34560
	v_cvt_pk_bf16_f32 v38, v4, v5
	v_cvt_pk_bf16_f32 v39, v6, v7
	v_mfma_f32_16x16x32_bf16 v[34:37], v[34:37], v[14:17], v[42:45]
	ds_bpermute_b32 v19, v33, v18
	s_waitcnt lgkmcnt(0)
	v_add_f32_e32 v18, v18, v19
	v_mfma_f32_16x16x32_bf16 v[14:17], v[0:3], v[38:41], v[8:11]
	ds_read_b64_tr_b16 v[0:1], v98 offset:32288
	ds_read_b64_tr_b16 v[2:3], v98 offset:34592
	ds_bpermute_b32 v19, v96, v18
	s_waitcnt lgkmcnt(0)
	v_add_f32_e32 v18, v18, v19
	v_mfma_f32_16x16x32_bf16 v[8:11], v[0:3], v[38:41], v[24:27]
	ds_read_b64_tr_b16 v[0:1], v98 offset:32320
	ds_read_b64_tr_b16 v[2:3], v98 offset:34624
	v_div_scale_f32 v19, s[22:23], v18, v18, 1.0
	s_waitcnt lgkmcnt(0)
	v_mfma_f32_16x16x32_bf16 v[4:7], v[0:3], v[38:41], v[34:37]
	ds_read_b64_tr_b16 v[0:1], v98 offset:32352
	ds_read_b64_tr_b16 v[2:3], v98 offset:34656
	s_waitcnt vmcnt(3)
	v_and_b32_e32 v24, 0xffff0000, v92
	s_waitcnt lgkmcnt(0)
	v_mfma_f32_16x16x32_bf16 v[0:3], v[0:3], v[38:41], v[20:23]
	s_nop 2
	v_rcp_f32_e32 v20, v19
	s_nop 0
	v_fma_f32 v21, -v19, v20, 1.0
	v_fmac_f32_e32 v20, v21, v20
	v_div_scale_f32 v21, vcc, 1.0, v18, 1.0
	v_mul_f32_e32 v22, v21, v20
	v_fma_f32 v23, -v19, v22, v21
	v_fmac_f32_e32 v22, v23, v20
	v_fma_f32 v19, -v19, v22, v21
	v_lshlrev_b32_e32 v21, 16, v92
	v_div_fmas_f32 v19, v19, v20, v22
	v_mul_f32_e32 v22, 0xbfb8aa3b, v21
	v_mul_f32_e32 v23, 0xbfb8aa3b, v24
	v_exp_f32_e32 v22, v22
	v_exp_f32_e32 v23, v23
	v_div_fixup_f32 v20, v19, v18, 1.0
	v_pk_mul_f32 v[14:15], v[20:21], v[14:15] op_sel_hi:[0,1]
	v_lshlrev_b64 v[18:19], 11, v[94:95]
	v_pk_add_f32 v[22:23], v[22:23], 1.0 op_sel_hi:[1,0]
	v_lshl_add_u64 v[18:19], v[80:81], 0, v[18:19]
	v_div_scale_f32 v25, s[22:23], v23, v23, v24
	v_rcp_f32_e32 v26, v25
	s_nop 0
	v_fma_f32 v27, -v25, v26, 1.0
	v_fmac_f32_e32 v26, v27, v26
	v_div_scale_f32 v27, vcc, v24, v23, v24
	v_mul_f32_e32 v28, v27, v26
	v_fma_f32 v29, -v25, v28, v27
	v_fmac_f32_e32 v28, v29, v26
	v_fma_f32 v25, -v25, v28, v27
	v_div_fmas_f32 v25, v25, v26, v28
	v_div_fixup_f32 v23, v25, v23, v24
	v_div_scale_f32 v24, s[22:23], v22, v22, v21
	v_rcp_f32_e32 v25, v24
	s_nop 0
	v_fma_f32 v26, -v24, v25, 1.0
	v_fmac_f32_e32 v25, v26, v25
	v_div_scale_f32 v26, vcc, v21, v22, v21
	v_mul_f32_e32 v27, v26, v25
	v_fma_f32 v28, -v24, v27, v26
	v_fmac_f32_e32 v27, v28, v25
	v_fma_f32 v24, -v24, v27, v26
	v_div_fmas_f32 v24, v24, v25, v27
	v_div_fixup_f32 v22, v24, v22, v21
	v_pk_mul_f32 v[14:15], v[22:23], v[14:15]
	v_and_b32_e32 v21, 0xffff0000, v93
	v_cvt_pk_bf16_f32 v14, v14, v15
	v_lshlrev_b32_e32 v15, 16, v93
	v_mul_f32_e32 v22, 0xbfb8aa3b, v15
	v_mul_f32_e32 v23, 0xbfb8aa3b, v21
	v_exp_f32_e32 v22, v22
	v_exp_f32_e32 v23, v23
	v_pk_mul_f32 v[16:17], v[20:21], v[16:17] op_sel_hi:[0,1]
	v_pk_add_f32 v[22:23], v[22:23], 1.0 op_sel_hi:[1,0]
	s_nop 0
	v_div_scale_f32 v24, s[22:23], v23, v23, v21
	v_rcp_f32_e32 v25, v24
	s_nop 0
	v_fma_f32 v26, -v24, v25, 1.0
	v_fmac_f32_e32 v25, v26, v25
	v_div_scale_f32 v26, vcc, v21, v23, v21
	v_mul_f32_e32 v27, v26, v25
	v_fma_f32 v28, -v24, v27, v26
	v_fmac_f32_e32 v27, v28, v25
	v_fma_f32 v24, -v24, v27, v26
	v_div_fmas_f32 v24, v24, v25, v27
	v_div_fixup_f32 v23, v24, v23, v21
	v_div_scale_f32 v21, s[22:23], v22, v22, v15
	v_rcp_f32_e32 v24, v21
	s_nop 0
	v_fma_f32 v25, -v21, v24, 1.0
	v_fmac_f32_e32 v24, v25, v24
	v_div_scale_f32 v25, vcc, v15, v22, v15
	v_mul_f32_e32 v26, v25, v24
	v_fma_f32 v27, -v21, v26, v25
	v_fmac_f32_e32 v26, v27, v24
	v_fma_f32 v21, -v21, v26, v25
	v_div_fmas_f32 v21, v21, v24, v26
	v_div_fixup_f32 v22, v21, v22, v15
	v_pk_mul_f32 v[16:17], v[22:23], v[16:17]
	v_pk_mul_f32 v[8:9], v[20:21], v[8:9] op_sel_hi:[0,1]
	v_cvt_pk_bf16_f32 v15, v16, v17
	s_waitcnt vmcnt(2)
	v_lshlrev_b32_e32 v16, 16, v90
	v_and_b32_e32 v17, 0xffff0000, v90
	global_store_dwordx2 v[18:19], v[14:15], off offset:1536
	v_mul_f32_e32 v14, 0xbfb8aa3b, v16
	v_mul_f32_e32 v15, 0xbfb8aa3b, v17
	v_exp_f32_e32 v14, v14
	v_exp_f32_e32 v15, v15
	s_nop 0
	v_pk_add_f32 v[14:15], v[14:15], 1.0 op_sel_hi:[1,0]
	s_nop 0
	v_div_scale_f32 v21, s[22:23], v15, v15, v17
	v_rcp_f32_e32 v22, v21
	s_nop 0
	v_fma_f32 v23, -v21, v22, 1.0
	v_fmac_f32_e32 v22, v23, v22
	v_div_scale_f32 v23, vcc, v17, v15, v17
	v_mul_f32_e32 v24, v23, v22
	v_fma_f32 v25, -v21, v24, v23
	v_fmac_f32_e32 v24, v25, v22
	v_fma_f32 v21, -v21, v24, v23
	v_div_fmas_f32 v21, v21, v22, v24
	v_div_fixup_f32 v15, v21, v15, v17
	v_div_scale_f32 v17, s[22:23], v14, v14, v16
	v_rcp_f32_e32 v21, v17
	s_nop 0
	v_fma_f32 v22, -v17, v21, 1.0
	v_fmac_f32_e32 v21, v22, v21
	v_div_scale_f32 v22, vcc, v16, v14, v16
	v_mul_f32_e32 v23, v22, v21
	v_fma_f32 v24, -v17, v23, v22
	v_fmac_f32_e32 v23, v24, v21
	v_fma_f32 v17, -v17, v23, v22
	v_div_fmas_f32 v17, v17, v21, v23
	v_div_fixup_f32 v14, v17, v14, v16
	v_pk_mul_f32 v[8:9], v[14:15], v[8:9]
	v_and_b32_e32 v16, 0xffff0000, v91
	v_cvt_pk_bf16_f32 v8, v8, v9
	v_lshlrev_b32_e32 v9, 16, v91
	v_mul_f32_e32 v14, 0xbfb8aa3b, v9
	v_mul_f32_e32 v15, 0xbfb8aa3b, v16
	v_exp_f32_e32 v14, v14
	v_exp_f32_e32 v15, v15
	v_pk_mul_f32 v[10:11], v[20:21], v[10:11] op_sel_hi:[0,1]
	v_pk_add_f32 v[14:15], v[14:15], 1.0 op_sel_hi:[1,0]
	s_nop 0
	v_div_scale_f32 v17, s[22:23], v15, v15, v16
	v_rcp_f32_e32 v21, v17
	s_nop 0
	v_fma_f32 v22, -v17, v21, 1.0
	v_fmac_f32_e32 v21, v22, v21
	v_div_scale_f32 v22, vcc, v16, v15, v16
	v_mul_f32_e32 v23, v22, v21
	v_fma_f32 v24, -v17, v23, v22
	v_fmac_f32_e32 v23, v24, v21
	v_fma_f32 v17, -v17, v23, v22
	v_div_fmas_f32 v17, v17, v21, v23
	v_div_fixup_f32 v15, v17, v15, v16
	v_div_scale_f32 v16, s[22:23], v14, v14, v9
	v_rcp_f32_e32 v17, v16
	s_nop 0
	v_fma_f32 v21, -v16, v17, 1.0
	v_fmac_f32_e32 v17, v21, v17
	v_div_scale_f32 v21, vcc, v9, v14, v9
	v_mul_f32_e32 v22, v21, v17
	v_fma_f32 v23, -v16, v22, v21
	v_fmac_f32_e32 v22, v23, v17
	v_fma_f32 v16, -v16, v22, v21
	v_div_fmas_f32 v16, v16, v17, v22
	v_div_fixup_f32 v14, v16, v14, v9
	v_pk_mul_f32 v[10:11], v[14:15], v[10:11]
	v_pk_mul_f32 v[4:5], v[20:21], v[4:5] op_sel_hi:[0,1]
	v_cvt_pk_bf16_f32 v9, v10, v11
	s_waitcnt vmcnt(2)
; #define LAS __attribute__((address_space(3)))
; DI unsigned cvt_pk_bf16(float lo, float hi) { const f32x2_t v = {lo, hi}; const bf16v2_t b = __builtin_convertvector(v, bf16v2_t); return __builtin_bit_cast(unsigned, b); }
; DI float bf_lo(unsigned u) { return __uint_as_float(u << 16); }
; DI float bf_hi(unsigned u) { return __uint_as_float(u & 0xffff0000u); }
; DI float silu_f(float x) { return x / (1.0f + __expf(-x)); }
; DI void mem_attn_item(ldsp lds, const bf16_t* proj, int ldp, int qmcol, int gatecol, const bf16_t* kv, bf16_t* branch, int b0, int item, int tid, int wid, int lane, const bool stage = true) {
;     ...
;     for (int i = 0; i < 4; ++i) {
;         const int e = tid + i * 512, row = e >> 3, ch = e & 7;
;         const u32x4 kx = *(const u32x4*)(kvb + (size_t)row * 2048 + ch * 8);
;         const u32x4 vx = *(const u32x4*)(kvb + (size_t)row * 2048 + 256 + ch * 8);
;         *(LAS u32x4*)(Kb + row * KS + ch * 16) = kx;
;         *(LAS u32x4*)(Vb + row * KS + ch * 16) = vx;
;     }
;     ...
;     const float inv = 1.0f / den;
;     bf16_t* dst = branch + ((size_t)(b0 + bl) * 2048 + tq) * 1024 + 768 + hm * 64 + quad * 4;
; #pragma unroll
;     for (int dt = 0; dt < 4; ++dt) {
;         const u32x2 gt = gtv[dt];
;         u32x2 o;
;         o.x = cvt_pk_bf16(oacc[dt][0] * inv * silu_f(bf_lo(gt.x)), oacc[dt][1] * inv * silu_f(bf_hi(gt.x)));
;         o.y = cvt_pk_bf16(oacc[dt][2] * inv * silu_f(bf_lo(gt.y)), oacc[dt][3] * inv * silu_f(bf_hi(gt.y)));
;         *(u32x2*)(dst + dt * 16) = o;
;     }
;     __syncthreads();
	v_lshlrev_b32_e32 v10, 16, v88
	v_and_b32_e32 v11, 0xffff0000, v88
	global_store_dwordx2 v[18:19], v[8:9], off offset:1568
	v_mul_f32_e32 v8, 0xbfb8aa3b, v10
	v_mul_f32_e32 v9, 0xbfb8aa3b, v11
	v_exp_f32_e32 v8, v8
	v_exp_f32_e32 v9, v9
	s_nop 0
	v_pk_add_f32 v[8:9], v[8:9], 1.0 op_sel_hi:[1,0]
	s_nop 0
	v_div_scale_f32 v14, s[22:23], v9, v9, v11
	v_rcp_f32_e32 v15, v14
	s_nop 0
	v_fma_f32 v16, -v14, v15, 1.0
	v_fmac_f32_e32 v15, v16, v15
	v_div_scale_f32 v16, vcc, v11, v9, v11
	v_mul_f32_e32 v17, v16, v15
	v_fma_f32 v21, -v14, v17, v16
	v_fmac_f32_e32 v17, v21, v15
	v_fma_f32 v14, -v14, v17, v16
	v_div_fmas_f32 v14, v14, v15, v17
	v_div_fixup_f32 v9, v14, v9, v11
	v_div_scale_f32 v11, s[22:23], v8, v8, v10
	v_rcp_f32_e32 v14, v11
	v_pk_mul_f32 v[6:7], v[20:21], v[6:7] op_sel_hi:[0,1]
	v_pk_mul_f32 v[0:1], v[20:21], v[0:1] op_sel_hi:[0,1]
	v_pk_mul_f32 v[2:3], v[20:21], v[2:3] op_sel_hi:[0,1]
	v_fma_f32 v15, -v11, v14, 1.0
	v_fmac_f32_e32 v14, v15, v14
	v_div_scale_f32 v15, vcc, v10, v8, v10
	v_mul_f32_e32 v16, v15, v14
	v_fma_f32 v17, -v11, v16, v15
	v_fmac_f32_e32 v16, v17, v14
	v_fma_f32 v11, -v11, v16, v15
	v_div_fmas_f32 v11, v11, v14, v16
	v_div_fixup_f32 v8, v11, v8, v10
	v_pk_mul_f32 v[4:5], v[8:9], v[4:5]
	v_and_b32_e32 v10, 0xffff0000, v89
	v_cvt_pk_bf16_f32 v4, v4, v5
	v_lshlrev_b32_e32 v5, 16, v89
	v_mul_f32_e32 v8, 0xbfb8aa3b, v5
	v_mul_f32_e32 v9, 0xbfb8aa3b, v10
	v_exp_f32_e32 v8, v8
	v_exp_f32_e32 v9, v9
	s_nop 0
	v_pk_add_f32 v[8:9], v[8:9], 1.0 op_sel_hi:[1,0]
	s_nop 0
	v_div_scale_f32 v11, s[22:23], v9, v9, v10
	v_rcp_f32_e32 v14, v11
	s_nop 0
	v_fma_f32 v15, -v11, v14, 1.0
	v_fmac_f32_e32 v14, v15, v14
	v_div_scale_f32 v15, vcc, v10, v9, v10
	v_mul_f32_e32 v16, v15, v14
	v_fma_f32 v17, -v11, v16, v15
	v_fmac_f32_e32 v16, v17, v14
	v_fma_f32 v11, -v11, v16, v15
	v_div_fmas_f32 v11, v11, v14, v16
	v_div_fixup_f32 v9, v11, v9, v10
	v_div_scale_f32 v10, s[22:23], v8, v8, v5
	v_rcp_f32_e32 v11, v10
	s_nop 0
	v_fma_f32 v14, -v10, v11, 1.0
	v_fmac_f32_e32 v11, v14, v11
	v_div_scale_f32 v14, vcc, v5, v8, v5
	v_mul_f32_e32 v15, v14, v11
	v_fma_f32 v16, -v10, v15, v14
	v_fmac_f32_e32 v15, v16, v11
	v_fma_f32 v10, -v10, v15, v14
	v_div_fmas_f32 v10, v10, v11, v15
	v_div_fixup_f32 v8, v10, v8, v5
	v_pk_mul_f32 v[6:7], v[8:9], v[6:7]
	s_nop 0
	v_cvt_pk_bf16_f32 v5, v6, v7
	s_waitcnt vmcnt(2)
	v_lshlrev_b32_e32 v6, 16, v86
	v_and_b32_e32 v7, 0xffff0000, v86
	global_store_dwordx2 v[18:19], v[4:5], off offset:1600
	v_mul_f32_e32 v4, 0xbfb8aa3b, v6
	v_mul_f32_e32 v5, 0xbfb8aa3b, v7
	v_exp_f32_e32 v4, v4
	v_exp_f32_e32 v5, v5
	s_nop 0
	v_pk_add_f32 v[4:5], v[4:5], 1.0 op_sel_hi:[1,0]
	s_nop 0
	v_div_scale_f32 v8, s[22:23], v5, v5, v7
	v_rcp_f32_e32 v9, v8
	s_nop 0
	v_fma_f32 v10, -v8, v9, 1.0
	v_fmac_f32_e32 v9, v10, v9
	v_div_scale_f32 v10, vcc, v7, v5, v7
	v_mul_f32_e32 v11, v10, v9
	v_fma_f32 v14, -v8, v11, v10
	v_fmac_f32_e32 v11, v14, v9
	v_fma_f32 v8, -v8, v11, v10
	v_div_fmas_f32 v8, v8, v9, v11
	v_div_fixup_f32 v5, v8, v5, v7
	v_div_scale_f32 v7, s[22:23], v4, v4, v6
	v_rcp_f32_e32 v8, v7
	s_nop 0
	v_fma_f32 v9, -v7, v8, 1.0
	v_fmac_f32_e32 v8, v9, v8
	v_div_scale_f32 v9, vcc, v6, v4, v6
	v_mul_f32_e32 v10, v9, v8
	v_fma_f32 v11, -v7, v10, v9
	v_fmac_f32_e32 v10, v11, v8
	v_fma_f32 v7, -v7, v10, v9
	v_div_fmas_f32 v7, v7, v8, v10
	v_div_fixup_f32 v4, v7, v4, v6
	v_pk_mul_f32 v[0:1], v[4:5], v[0:1]
	v_and_b32_e32 v6, 0xffff0000, v87
	v_cvt_pk_bf16_f32 v0, v0, v1
	v_lshlrev_b32_e32 v1, 16, v87
	v_mul_f32_e32 v4, 0xbfb8aa3b, v1
	v_mul_f32_e32 v5, 0xbfb8aa3b, v6
	v_exp_f32_e32 v4, v4
	v_exp_f32_e32 v5, v5
	s_nop 0
	v_pk_add_f32 v[4:5], v[4:5], 1.0 op_sel_hi:[1,0]
	s_nop 0
	v_div_scale_f32 v7, s[22:23], v5, v5, v6
	v_rcp_f32_e32 v8, v7
	s_nop 0
	v_fma_f32 v9, -v7, v8, 1.0
	v_fmac_f32_e32 v8, v9, v8
	v_div_scale_f32 v9, vcc, v6, v5, v6
	v_mul_f32_e32 v10, v9, v8
	v_fma_f32 v11, -v7, v10, v9
	v_fmac_f32_e32 v10, v11, v8
	v_fma_f32 v7, -v7, v10, v9
	v_div_fmas_f32 v7, v7, v8, v10
	v_div_fixup_f32 v5, v7, v5, v6
	v_div_scale_f32 v6, s[22:23], v4, v4, v1
	v_rcp_f32_e32 v7, v6
	s_nop 0
	v_fma_f32 v8, -v6, v7, 1.0
	v_fmac_f32_e32 v7, v8, v7
	v_div_scale_f32 v8, vcc, v1, v4, v1
	v_mul_f32_e32 v9, v8, v7
	v_fma_f32 v10, -v6, v9, v8
	v_fmac_f32_e32 v9, v10, v7
	v_fma_f32 v6, -v6, v9, v8
	v_div_fmas_f32 v6, v6, v7, v9
	v_div_fixup_f32 v4, v6, v4, v1
	v_pk_mul_f32 v[2:3], v[4:5], v[2:3]
	s_nop 0
	v_cvt_pk_bf16_f32 v1, v2, v3
	global_store_dwordx2 v[18:19], v[0:1], off offset:1632
	s_cbranch_scc0 .Lma_cont_gla
	s_barrier
	s_branch .LBB0_514
.Lma_cont_gla:
.LBB0_512:
	s_cmp_lg_u32 s14, 0
	s_mov_b64 s[26:27], 0x1420
	s_cbranch_scc1 .LBB0_511
	global_load_dwordx4 v[34:37], v[30:31], off
	global_load_dwordx4 v[38:41], v[30:31], off offset:512
	global_load_dwordx4 v[42:45], v[74:75], off
	global_load_dwordx4 v[46:49], v[74:75], off offset:512
	global_load_dwordx4 v[50:53], v[76:77], off
	global_load_dwordx4 v[54:57], v[76:77], off offset:512
	global_load_dwordx4 v[58:61], v[78:79], off
	global_load_dwordx4 v[62:65], v[78:79], off offset:512
	s_waitcnt vmcnt(7)
	ds_write_b128 v99, v[34:37]
	s_waitcnt vmcnt(6)
	ds_write_b128 v99, v[38:41] offset:36864
	s_waitcnt vmcnt(5)
	ds_write_b128 v100, v[42:45]
	s_waitcnt vmcnt(4)
	ds_write_b128 v100, v[46:49] offset:36864
	s_waitcnt vmcnt(3)
	ds_write_b128 v101, v[50:53]
	s_waitcnt vmcnt(2)
	ds_write_b128 v101, v[54:57] offset:36864
	s_waitcnt vmcnt(1)
	ds_write_b128 v102, v[58:61]
	s_waitcnt vmcnt(0)
	ds_write_b128 v102, v[62:65] offset:36864
	s_branch .LBB0_511

; DI unsigned xb_ld(unsigned* p)              { return __hip_atomic_load(p, __ATOMIC_RELAXED, __HIP_MEMORY_SCOPE_AGENT); }
; DI unsigned xb_add(unsigned* p, unsigned v) { return __hip_atomic_fetch_add(p, v, __ATOMIC_RELAXED, __HIP_MEMORY_SCOPE_AGENT); }
; #define XB_SPIN(cond, bar) do { unsigned _sp = 0; while (cond) { __builtin_amdgcn_s_sleep(1); \
;     if ((++_sp & 255u) == 0u) { if (xb_ld(&(bar)[XB_TMO])) break; if (_sp > XB_SPIN_CAP) { atomicAdd(&(bar)[XB_TMO], 1u); break; } } } } while (0)
; DI void xcd_barrier(const XcdBarrier& b) {
;     ...
;         unsigned nloc = b.st[0], nx = b.st[1];
;         if (nloc == 0u) { xcd_barrier_complete(bar, b.x, nloc, nx); b.st[0] = nloc; b.st[1] = nx; }
;         const unsigned old = xb_add(&bar[XB_XSUB(b.x)], 1u);
;         const unsigned gen = old / nloc;
;         if (old + 1u == (gen + 1u) * nloc) {
;             __builtin_amdgcn_fence(__ATOMIC_RELEASE, "agent");
;             asm volatile("s_waitcnt vmcnt(0)" ::: "memory");
;             const unsigned og = xb_add(&bar[XB_TOP], 1u);
;             const unsigned tg = og / nx;
;             if (og + 1u == (tg + 1u) * nx) xb_add(&bar[XB_TOPGEN], 1u);
;             else XB_SPIN(xb_ld(&bar[XB_TOPGEN]) == tg, bar);
;             __builtin_amdgcn_fence(__ATOMIC_ACQUIRE, "agent");
;             xb_add(&bar[XB_XGEN(b.x)], 1u);
;             asm volatile("s_waitcnt vmcnt(0)" ::: "memory");
;         } else {
;             XB_SPIN(xb_ld(&bar[XB_XGEN(b.x)]) == gen, bar);
.LBB0_1151:
	s_or_b64 exec, exec, s[16:17]
	v_cvt_f32_u32_e32 v4, v2
	s_waitcnt vmcnt(0)
	v_readfirstlane_b32 s0, v3
	v_sub_u32_e32 v3, 0, v2
	v_rcp_iflag_f32_e32 v4, v4
	v_add_u32_e32 v5, s0, v1
	v_mul_f32_e32 v4, 0x4f7ffffe, v4
	v_cvt_u32_f32_e32 v4, v4
	v_mul_lo_u32 v1, v3, v4
	v_mul_hi_u32 v1, v4, v1
	v_add_u32_e32 v1, v4, v1
	v_mul_hi_u32 v1, v5, v1
	v_mul_lo_u32 v3, v1, v2
	v_sub_u32_e32 v3, v5, v3
	v_add_u32_e32 v4, 1, v1
	v_cmp_ge_u32_e32 vcc, v3, v2
	s_nop 1
	v_cndmask_b32_e32 v1, v1, v4, vcc
	v_sub_u32_e32 v4, v3, v2
	v_cndmask_b32_e32 v3, v3, v4, vcc
	v_add_u32_e32 v4, 1, v1
	v_cmp_ge_u32_e32 vcc, v3, v2
	v_add_u32_e32 v3, 1, v5
	s_nop 0
	v_cndmask_b32_e32 v1, v1, v4, vcc
	v_mul_lo_u32 v4, v2, v1
	v_add_u32_e32 v2, v4, v2
	v_cmp_ne_u32_e32 vcc, v3, v2
	s_and_saveexec_b64 s[16:17], vcc
	s_xor_b64 s[16:17], exec, s[16:17]
	s_cbranch_execz .LBB0_1165
	v_readlane_b32 s18, v253, 40
	v_readlane_b32 s19, v253, 41
	s_waitcnt lgkmcnt(0)
	s_nop 3
	global_load_dword v0, v12, s[18:19] sc1
	s_waitcnt vmcnt(0)
	v_cmp_eq_u32_e32 vcc, v0, v1
	s_and_saveexec_b64 s[18:19], vcc
	s_cbranch_execz .LBB0_1164
	s_mov_b32 s0, 1
	s_mov_b64 s[26:27], 0
	s_branch .LBB0_1155

; DI unsigned xb_ld(unsigned* p)              { return __hip_atomic_load(p, __ATOMIC_RELAXED, __HIP_MEMORY_SCOPE_AGENT); }
; #define XB_SPIN(cond, bar) do { unsigned _sp = 0; while (cond) { __builtin_amdgcn_s_sleep(1); \
;     if ((++_sp & 255u) == 0u) { if (xb_ld(&(bar)[XB_TMO])) break; if (_sp > XB_SPIN_CAP) { atomicAdd(&(bar)[XB_TMO], 1u); break; } } } } while (0)
; DI void xcd_barrier(const XcdBarrier& b) {
;     ...
;             XB_SPIN(xb_ld(&bar[XB_XGEN(b.x)]) == gen, bar);
.LBB0_1159:
	v_readlane_b32 s22, v253, 40
	v_readlane_b32 s23, v253, 41
	s_add_i32 s0, s0, 1
	s_mov_b64 s[34:35], -1
	s_nop 2
	global_load_dword v0, v12, s[22:23] sc1
	s_waitcnt vmcnt(0)
	v_cmp_ne_u32_e32 vcc, v0, v1
	s_orn2_b64 s[36:37], vcc, exec
	s_branch .LBB0_1154

; DI unsigned xb_ld(unsigned* p)              { return __hip_atomic_load(p, __ATOMIC_RELAXED, __HIP_MEMORY_SCOPE_AGENT); }
; DI unsigned xb_add(unsigned* p, unsigned v) { return __hip_atomic_fetch_add(p, v, __ATOMIC_RELAXED, __HIP_MEMORY_SCOPE_AGENT); }
; #define XB_SPIN(cond, bar) do { unsigned _sp = 0; while (cond) { __builtin_amdgcn_s_sleep(1); \
;     if ((++_sp & 255u) == 0u) { if (xb_ld(&(bar)[XB_TMO])) break; if (_sp > XB_SPIN_CAP) { atomicAdd(&(bar)[XB_TMO], 1u); break; } } } } while (0)
; DI void xcd_barrier(const XcdBarrier& b) {
;     ...
;             __builtin_amdgcn_fence(__ATOMIC_RELEASE, "agent");
;             asm volatile("s_waitcnt vmcnt(0)" ::: "memory");
;             const unsigned og = xb_add(&bar[XB_TOP], 1u);
;             const unsigned tg = og / nx;
;             if (og + 1u == (tg + 1u) * nx) xb_add(&bar[XB_TOPGEN], 1u);
;             else XB_SPIN(xb_ld(&bar[XB_TOPGEN]) == tg, bar);
;             __builtin_amdgcn_fence(__ATOMIC_ACQUIRE, "agent");
;             xb_add(&bar[XB_XGEN(b.x)], 1u);
;             asm volatile("s_waitcnt vmcnt(0)" ::: "memory");
.LBB0_1182:
	s_or_b64 exec, exec, s[16:17]
	s_mov_b64 s[16:17], exec
	v_mbcnt_lo_u32_b32 v0, s16, 0
	v_mbcnt_hi_u32_b32 v0, s17, v0
	v_cmp_eq_u32_e32 vcc, 0, v0
	s_waitcnt vmcnt(0)
	buffer_inv sc1
	s_and_saveexec_b64 s[18:19], vcc
	s_cbranch_execz .LBB0_1184
.LBB0_1184:
	s_or_b64 exec, exec, s[18:19]
	s_waitcnt vmcnt(0)
